# baseline (speedup 1.0000x reference)
; __device__ __forceinline__ float siluf(float x) { return x * __builtin_amdgcn_rcpf(1.f + __expf(-x)); }
; #define STAGE_TILE_F(XFORM) do { SW_BEGIN f32x4 v = acc[ai][bj][m][n2]; XFORM; \
;     *(u32x2*)(smem + mrow * SPITCH + nc0 * 2) = u32x2{cvtpk_t(v[0], v[1]), cvtpk_t(v[2], v[3])}; LOOP_END __syncthreads(); } while (0)
; template <int kind> __device__ __forceinline__ void gemm_phase_n(const Params& P, int layer, int b, const int wv) {
;     ...
;                 } else if (pn < 12) {
;                     STAGE_TILE_F(const float r = rs_lds[mrow]; v[0] = siluf(v[0] * r); v[1] = siluf(v[1] * r); v[2] = siluf(v[2] * r); v[3] = siluf(v[3] * r));
;                     u16* dst = (u16*)(ws + O_SG) + (size_t)t0 * 2048 + (pn - 4) * 256;
;                     DRAIN_BEGIN *(u32x4*)(dst + (size_t)row * 2048 + chunk * 8) = w; LOOP_END
.LBB0_682:
	s_andn2_b64 vcc, exec, s[2:3]
	s_cbranch_vccnz .LBB0_685
	v_lshl_or_b32 v134, v140, 5, v141
	v_lshl_add_u32 v0, v134, 2, 0
	v_add_u32_e32 v0, 0x22000, v0
	ds_read_b32 v148, v0
	ds_read_b32 v149, v0 offset:64
	ds_read_b32 v150, v0 offset:512
	ds_read_b32 v151, v0 offset:576
	s_waitcnt lgkmcnt(0)
	v_mov_b32_e32 v132, v148
	v_lshlrev_b32_e32 v130, 7, v142
	v_lshl_add_u32 v131, v143, 3, 0
	v_mul_u32_u24_e32 v134, 0x220, v134
	v_add3_u32 v131, v131, v130, v134
	v_mul_f32_e32 v133, v126, v132
	v_mul_f32_e32 v135, 0xbfb8aa3b, v133
	v_exp_f32_e32 v135, v135
	s_lshl_b64 s[2:3], s[10:11], 12
	v_add_f32_e32 v135, 1.0, v135
	v_rcp_f32_e32 v135, v135
	s_nop 0
	v_mul_f32_e32 v133, v133, v135
	v_mul_f32_e32 v135, v127, v132
	v_mul_f32_e32 v136, 0xbfb8aa3b, v135
	v_exp_f32_e32 v136, v136
	s_nop 0
	v_add_f32_e32 v136, 1.0, v136
	v_rcp_f32_e32 v136, v136
	s_nop 0
	v_mul_f32_e32 v135, v135, v136
	v_mul_f32_e32 v136, v128, v132
	v_mul_f32_e32 v138, 0xbfb8aa3b, v136
	v_exp_f32_e32 v138, v138
	v_mul_f32_e32 v132, v129, v132
	v_add_f32_e32 v138, 1.0, v138
	v_rcp_f32_e32 v138, v138
	s_nop 0
	v_mul_f32_e32 v136, v136, v138
	v_mul_f32_e32 v138, 0xbfb8aa3b, v132
	v_exp_f32_e32 v138, v138
	s_nop 0
	v_add_f32_e32 v138, 1.0, v138
	v_rcp_f32_e32 v138, v138
	s_nop 0
	v_mul_f32_e32 v138, v132, v138
	s_nop 0
	v_cvt_pk_bf16_f32 v132, v133, v135
	s_nop 0
	v_cvt_pk_bf16_f32 v133, v136, v138
	ds_write_b64 v131, v[132:133]
	v_mov_b32_e32 v130, v149
	v_mul_f32_e32 v132, v118, v130
	v_mul_f32_e32 v133, 0xbfb8aa3b, v132
	v_exp_f32_e32 v133, v133
	s_nop 0
	v_add_f32_e32 v133, 1.0, v133
	v_rcp_f32_e32 v133, v133
	s_nop 0
	v_mul_f32_e32 v132, v132, v133
	v_mul_f32_e32 v133, v119, v130
	v_mul_f32_e32 v134, 0xbfb8aa3b, v133
	v_exp_f32_e32 v134, v134
	s_nop 0
	v_add_f32_e32 v134, 1.0, v134
	v_rcp_f32_e32 v134, v134
	s_nop 0
	v_mul_f32_e32 v133, v133, v134
	v_mul_f32_e32 v134, v120, v130
	v_mul_f32_e32 v135, 0xbfb8aa3b, v134
	v_exp_f32_e32 v135, v135
	v_mul_f32_e32 v130, v121, v130
	s_nop 0
	v_cvt_pk_bf16_f32 v132, v132, v133
	v_add_f32_e32 v135, 1.0, v135
	v_rcp_f32_e32 v135, v135
	s_nop 0
	v_mul_f32_e32 v134, v134, v135
	v_mul_f32_e32 v135, 0xbfb8aa3b, v130
	v_exp_f32_e32 v135, v135
	s_nop 0
	v_add_f32_e32 v135, 1.0, v135
	v_rcp_f32_e32 v135, v135
	s_nop 0
	v_mul_f32_e32 v130, v130, v135
	s_nop 0
	v_cvt_pk_bf16_f32 v133, v134, v130
	ds_write_b64 v131, v[132:133] offset:8704
	v_mov_b32_e32 v132, v150
	v_add_u32_e32 v130, 0x2200, v131
	v_mul_f32_e32 v133, v122, v132
	v_mul_f32_e32 v134, 0xbfb8aa3b, v133
	v_exp_f32_e32 v134, v134
	s_nop 0
	v_add_f32_e32 v134, 1.0, v134
	v_rcp_f32_e32 v134, v134
	s_nop 0
	v_mul_f32_e32 v133, v133, v134
	v_mul_f32_e32 v134, v123, v132
	v_mul_f32_e32 v135, 0xbfb8aa3b, v134
	v_exp_f32_e32 v135, v135
	s_nop 0
	v_add_f32_e32 v135, 1.0, v135
	v_rcp_f32_e32 v135, v135
	s_nop 0
	v_mul_f32_e32 v134, v134, v135
	v_mul_f32_e32 v135, v124, v132
	v_mul_f32_e32 v136, 0xbfb8aa3b, v135
	v_exp_f32_e32 v136, v136
	v_mul_f32_e32 v132, v125, v132
	s_nop 0
	v_cvt_pk_bf16_f32 v134, v133, v134
	v_add_f32_e32 v136, 1.0, v136
	v_rcp_f32_e32 v136, v136
	s_nop 0
	v_mul_f32_e32 v135, v135, v136
	v_mul_f32_e32 v136, 0xbfb8aa3b, v132
	v_exp_f32_e32 v136, v136
	s_nop 0
	v_add_f32_e32 v136, 1.0, v136
	v_rcp_f32_e32 v136, v136
	s_nop 0
	v_mul_f32_e32 v132, v132, v136
	s_nop 0
	v_cvt_pk_bf16_f32 v135, v135, v132
	ds_write_b64 v130, v[134:135] offset:60928
	v_mov_b32_e32 v133, v151
	v_add_u32_e32 v132, 0xee00, v130
	v_mul_f32_e32 v134, v114, v133
	v_mul_f32_e32 v135, 0xbfb8aa3b, v134
	v_exp_f32_e32 v135, v135
	s_nop 0
	v_add_f32_e32 v135, 1.0, v135
	v_rcp_f32_e32 v135, v135
	s_nop 0
	v_mul_f32_e32 v134, v134, v135
	v_mul_f32_e32 v135, v115, v133
	v_mul_f32_e32 v136, 0xbfb8aa3b, v135
	v_exp_f32_e32 v136, v136
	s_nop 0
	v_add_f32_e32 v136, 1.0, v136
	v_rcp_f32_e32 v136, v136
	s_nop 0
	v_mul_f32_e32 v135, v135, v136
	v_mul_f32_e32 v136, v116, v133
	v_mul_f32_e32 v138, 0xbfb8aa3b, v136
	v_exp_f32_e32 v138, v138
	v_mul_f32_e32 v133, v117, v133
	s_nop 0
	v_cvt_pk_bf16_f32 v134, v134, v135
	v_add_f32_e32 v138, 1.0, v138
	v_rcp_f32_e32 v138, v138
	s_nop 0
	v_mul_f32_e32 v136, v136, v138
	v_mul_f32_e32 v138, 0xbfb8aa3b, v133
	v_exp_f32_e32 v138, v138
	s_nop 0
	v_add_f32_e32 v138, 1.0, v138
	v_rcp_f32_e32 v138, v138
	s_nop 0
	v_mul_f32_e32 v133, v133, v138
	s_nop 0
	v_cvt_pk_bf16_f32 v135, v136, v133
	ds_write_b64 v132, v[134:135] offset:8704
	v_mov_b32_e32 v133, v148
	v_mul_f32_e32 v134, v110, v133
	v_mul_f32_e32 v135, 0xbfb8aa3b, v134
	v_exp_f32_e32 v135, v135
	s_nop 0
	v_add_f32_e32 v135, 1.0, v135
	v_rcp_f32_e32 v135, v135
	s_nop 0
	v_mul_f32_e32 v134, v134, v135
	v_mul_f32_e32 v135, v111, v133
	v_mul_f32_e32 v136, 0xbfb8aa3b, v135
	v_exp_f32_e32 v136, v136
	s_nop 0
	v_add_f32_e32 v136, 1.0, v136
	v_rcp_f32_e32 v136, v136
	s_nop 0
	v_mul_f32_e32 v135, v135, v136
	v_mul_f32_e32 v136, v112, v133
	v_mul_f32_e32 v138, 0xbfb8aa3b, v136
	v_exp_f32_e32 v138, v138
	v_mul_f32_e32 v133, v113, v133
	s_nop 0
	v_cvt_pk_bf16_f32 v134, v134, v135
	v_add_f32_e32 v138, 1.0, v138
	v_rcp_f32_e32 v138, v138
	s_nop 0
	v_mul_f32_e32 v136, v136, v138
	v_mul_f32_e32 v138, 0xbfb8aa3b, v133
	v_exp_f32_e32 v138, v138
	s_nop 0
	v_add_f32_e32 v138, 1.0, v138
	v_rcp_f32_e32 v138, v138
	s_nop 0
	v_mul_f32_e32 v133, v133, v138
	s_nop 0
	v_cvt_pk_bf16_f32 v135, v136, v133
	ds_write_b64 v131, v[134:135] offset:32
	v_mov_b32_e32 v133, v149
	v_mul_f32_e32 v134, v102, v133
	v_mul_f32_e32 v135, 0xbfb8aa3b, v134
	v_exp_f32_e32 v135, v135
	s_nop 0
	v_add_f32_e32 v135, 1.0, v135
	v_rcp_f32_e32 v135, v135
	s_nop 0
	v_mul_f32_e32 v134, v134, v135
	v_mul_f32_e32 v135, v103, v133
	v_mul_f32_e32 v136, 0xbfb8aa3b, v135
; __device__ __forceinline__ float siluf(float x) { return x * __builtin_amdgcn_rcpf(1.f + __expf(-x)); }
; #define STAGE_TILE_F(XFORM) do { SW_BEGIN f32x4 v = acc[ai][bj][m][n2]; XFORM; \
;     *(u32x2*)(smem + mrow * SPITCH + nc0 * 2) = u32x2{cvtpk_t(v[0], v[1]), cvtpk_t(v[2], v[3])}; LOOP_END __syncthreads(); } while (0)
; template <int kind> __device__ __forceinline__ void gemm_phase_n(const Params& P, int layer, int b, const int wv) {
;     ...
;                 } else if (pn < 12) {
;                     STAGE_TILE_F(const float r = rs_lds[mrow]; v[0] = siluf(v[0] * r); v[1] = siluf(v[1] * r); v[2] = siluf(v[2] * r); v[3] = siluf(v[3] * r));
;                     u16* dst = (u16*)(ws + O_SG) + (size_t)t0 * 2048 + (pn - 4) * 256;
;                     DRAIN_BEGIN *(u32x4*)(dst + (size_t)row * 2048 + chunk * 8) = w; LOOP_END
	v_exp_f32_e32 v136, v136
	s_nop 0
	v_add_f32_e32 v136, 1.0, v136
	v_rcp_f32_e32 v136, v136
	s_nop 0
	v_mul_f32_e32 v135, v135, v136
	v_mul_f32_e32 v136, v104, v133
	v_mul_f32_e32 v138, 0xbfb8aa3b, v136
	v_exp_f32_e32 v138, v138
	v_mul_f32_e32 v133, v105, v133
	s_nop 0
	v_cvt_pk_bf16_f32 v134, v134, v135
	v_add_f32_e32 v138, 1.0, v138
	v_rcp_f32_e32 v138, v138
	s_nop 0
	v_mul_f32_e32 v136, v136, v138
	v_mul_f32_e32 v138, 0xbfb8aa3b, v133
	v_exp_f32_e32 v138, v138
	s_nop 0
	v_add_f32_e32 v138, 1.0, v138
	v_rcp_f32_e32 v138, v138
	s_nop 0
	v_mul_f32_e32 v133, v133, v138
	s_nop 0
	v_cvt_pk_bf16_f32 v135, v136, v133
	ds_write_b64 v131, v[134:135] offset:8736
	v_mov_b32_e32 v133, v150
	v_mul_f32_e32 v134, v106, v133
	v_mul_f32_e32 v135, 0xbfb8aa3b, v134
	v_exp_f32_e32 v135, v135
	s_nop 0
	v_add_f32_e32 v135, 1.0, v135
	v_rcp_f32_e32 v135, v135
	s_nop 0
	v_mul_f32_e32 v134, v134, v135
	v_mul_f32_e32 v135, v107, v133
	v_mul_f32_e32 v136, 0xbfb8aa3b, v135
	v_exp_f32_e32 v136, v136
	s_nop 0
	v_add_f32_e32 v136, 1.0, v136
	v_rcp_f32_e32 v136, v136
	s_nop 0
	v_mul_f32_e32 v135, v135, v136
	v_mul_f32_e32 v136, v108, v133
	v_mul_f32_e32 v138, 0xbfb8aa3b, v136
	v_exp_f32_e32 v138, v138
	v_mul_f32_e32 v133, v109, v133
	s_nop 0
	v_cvt_pk_bf16_f32 v134, v134, v135
	v_add_f32_e32 v138, 1.0, v138
	v_rcp_f32_e32 v138, v138
	s_nop 0
	v_mul_f32_e32 v136, v136, v138
	v_mul_f32_e32 v138, 0xbfb8aa3b, v133
	v_exp_f32_e32 v138, v138
	s_nop 0
	v_add_f32_e32 v138, 1.0, v138
	v_rcp_f32_e32 v138, v138
	s_nop 0
	v_mul_f32_e32 v133, v133, v138
	s_nop 0
	v_cvt_pk_bf16_f32 v135, v136, v133
	ds_write_b64 v130, v[134:135] offset:60960
	v_mov_b32_e32 v133, v151
	v_mul_f32_e32 v134, v98, v133
	v_mul_f32_e32 v135, 0xbfb8aa3b, v134
	v_exp_f32_e32 v135, v135
	s_nop 0
	v_add_f32_e32 v135, 1.0, v135
	v_rcp_f32_e32 v135, v135
	s_nop 0
	v_mul_f32_e32 v134, v134, v135
	v_mul_f32_e32 v135, v99, v133
	v_mul_f32_e32 v136, 0xbfb8aa3b, v135
	v_exp_f32_e32 v136, v136
	s_nop 0
	v_add_f32_e32 v136, 1.0, v136
	v_rcp_f32_e32 v136, v136
	s_nop 0
	v_mul_f32_e32 v135, v135, v136
	v_mul_f32_e32 v136, v100, v133
	v_mul_f32_e32 v138, 0xbfb8aa3b, v136
	v_exp_f32_e32 v138, v138
	v_mul_f32_e32 v133, v101, v133
	s_nop 0
	v_cvt_pk_bf16_f32 v134, v134, v135
	v_add_f32_e32 v138, 1.0, v138
	v_rcp_f32_e32 v138, v138
	s_nop 0
	v_mul_f32_e32 v136, v136, v138
	v_mul_f32_e32 v138, 0xbfb8aa3b, v133
	v_exp_f32_e32 v138, v138
	s_nop 0
	v_add_f32_e32 v138, 1.0, v138
	v_rcp_f32_e32 v138, v138
	s_nop 0
	v_mul_f32_e32 v133, v133, v138
	s_nop 0
	v_cvt_pk_bf16_f32 v135, v136, v133
	ds_write_b64 v132, v[134:135] offset:8736
	v_mov_b32_e32 v133, v148
	v_mul_f32_e32 v134, v94, v133
	v_mul_f32_e32 v135, 0xbfb8aa3b, v134
	v_exp_f32_e32 v135, v135
	s_nop 0
	v_add_f32_e32 v135, 1.0, v135
	v_rcp_f32_e32 v135, v135
	s_nop 0
	v_mul_f32_e32 v134, v134, v135
	v_mul_f32_e32 v135, v95, v133
	v_mul_f32_e32 v136, 0xbfb8aa3b, v135
	v_exp_f32_e32 v136, v136
	s_nop 0
	v_add_f32_e32 v136, 1.0, v136
	v_rcp_f32_e32 v136, v136
	s_nop 0
	v_mul_f32_e32 v135, v135, v136
	v_mul_f32_e32 v136, v96, v133
	v_mul_f32_e32 v138, 0xbfb8aa3b, v136
	v_exp_f32_e32 v138, v138
	v_mul_f32_e32 v133, v97, v133
	s_nop 0
	v_cvt_pk_bf16_f32 v134, v134, v135
	v_add_f32_e32 v138, 1.0, v138
	v_rcp_f32_e32 v138, v138
	s_nop 0
	v_mul_f32_e32 v136, v136, v138
	v_mul_f32_e32 v138, 0xbfb8aa3b, v133
	v_exp_f32_e32 v138, v138
	s_nop 0
	v_add_f32_e32 v138, 1.0, v138
	v_rcp_f32_e32 v138, v138
	s_nop 0
	v_mul_f32_e32 v133, v133, v138
	s_nop 0
	v_cvt_pk_bf16_f32 v135, v136, v133
	ds_write_b64 v131, v[134:135] offset:64
	v_mov_b32_e32 v133, v149
	v_mul_f32_e32 v134, v86, v133
	v_mul_f32_e32 v135, 0xbfb8aa3b, v134
	v_exp_f32_e32 v135, v135
	s_nop 0
	v_add_f32_e32 v135, 1.0, v135
	v_rcp_f32_e32 v135, v135
	s_nop 0
	v_mul_f32_e32 v134, v134, v135
	v_mul_f32_e32 v135, v87, v133
	v_mul_f32_e32 v136, 0xbfb8aa3b, v135
	v_exp_f32_e32 v136, v136
	s_nop 0
	v_add_f32_e32 v136, 1.0, v136
	v_rcp_f32_e32 v136, v136
	s_nop 0
	v_mul_f32_e32 v135, v135, v136
	v_mul_f32_e32 v136, v88, v133
	v_mul_f32_e32 v138, 0xbfb8aa3b, v136
	v_exp_f32_e32 v138, v138
	v_mul_f32_e32 v133, v89, v133
	s_nop 0
	v_cvt_pk_bf16_f32 v134, v134, v135
	v_add_f32_e32 v138, 1.0, v138
	v_rcp_f32_e32 v138, v138
	s_nop 0
	v_mul_f32_e32 v136, v136, v138
	v_mul_f32_e32 v138, 0xbfb8aa3b, v133
	v_exp_f32_e32 v138, v138
	s_nop 0
	v_add_f32_e32 v138, 1.0, v138
	v_rcp_f32_e32 v138, v138
	s_nop 0
	v_mul_f32_e32 v133, v133, v138
	s_nop 0
	v_cvt_pk_bf16_f32 v135, v136, v133
	ds_write_b64 v131, v[134:135] offset:8768
	v_mov_b32_e32 v133, v150
	v_mul_f32_e32 v134, v90, v133
	v_mul_f32_e32 v135, 0xbfb8aa3b, v134
	v_exp_f32_e32 v135, v135
	s_nop 0
	v_add_f32_e32 v135, 1.0, v135
	v_rcp_f32_e32 v135, v135
	s_nop 0
	v_mul_f32_e32 v134, v134, v135
	v_mul_f32_e32 v135, v91, v133
	v_mul_f32_e32 v136, 0xbfb8aa3b, v135
	v_exp_f32_e32 v136, v136
	s_nop 0
	v_add_f32_e32 v136, 1.0, v136
	v_rcp_f32_e32 v136, v136
	s_nop 0
	v_mul_f32_e32 v135, v135, v136
	v_mul_f32_e32 v136, v92, v133
	v_mul_f32_e32 v138, 0xbfb8aa3b, v136
	v_exp_f32_e32 v138, v138
	v_mul_f32_e32 v133, v93, v133
	s_nop 0
	v_cvt_pk_bf16_f32 v134, v134, v135
	v_add_f32_e32 v138, 1.0, v138
	v_rcp_f32_e32 v138, v138
	s_nop 0
	v_mul_f32_e32 v136, v136, v138
	v_mul_f32_e32 v138, 0xbfb8aa3b, v133
	v_exp_f32_e32 v138, v138
	s_nop 0
	v_add_f32_e32 v138, 1.0, v138
	v_rcp_f32_e32 v138, v138
	s_nop 0
	v_mul_f32_e32 v133, v133, v138
	s_nop 0
	v_cvt_pk_bf16_f32 v135, v136, v133
	ds_write_b64 v130, v[134:135] offset:60992
	v_mov_b32_e32 v133, v151
	v_mul_f32_e32 v134, v82, v133
	v_mul_f32_e32 v135, 0xbfb8aa3b, v134
	v_exp_f32_e32 v135, v135
	s_nop 0
	v_add_f32_e32 v135, 1.0, v135
	v_rcp_f32_e32 v135, v135
; __device__ __forceinline__ float siluf(float x) { return x * __builtin_amdgcn_rcpf(1.f + __expf(-x)); }
; #define STAGE_TILE_F(XFORM) do { SW_BEGIN f32x4 v = acc[ai][bj][m][n2]; XFORM; \
;     *(u32x2*)(smem + mrow * SPITCH + nc0 * 2) = u32x2{cvtpk_t(v[0], v[1]), cvtpk_t(v[2], v[3])}; LOOP_END __syncthreads(); } while (0)
; template <int kind> __device__ __forceinline__ void gemm_phase_n(const Params& P, int layer, int b, const int wv) {
;     ...
;                 } else if (pn < 12) {
;                     STAGE_TILE_F(const float r = rs_lds[mrow]; v[0] = siluf(v[0] * r); v[1] = siluf(v[1] * r); v[2] = siluf(v[2] * r); v[3] = siluf(v[3] * r));
;                     u16* dst = (u16*)(ws + O_SG) + (size_t)t0 * 2048 + (pn - 4) * 256;
;                     DRAIN_BEGIN *(u32x4*)(dst + (size_t)row * 2048 + chunk * 8) = w; LOOP_END
	s_nop 0
	v_mul_f32_e32 v134, v134, v135
	v_mul_f32_e32 v135, v83, v133
	v_mul_f32_e32 v136, 0xbfb8aa3b, v135
	v_exp_f32_e32 v136, v136
	s_nop 0
	v_add_f32_e32 v136, 1.0, v136
	v_rcp_f32_e32 v136, v136
	s_nop 0
	v_mul_f32_e32 v135, v135, v136
	v_mul_f32_e32 v136, v84, v133
	v_mul_f32_e32 v138, 0xbfb8aa3b, v136
	v_exp_f32_e32 v138, v138
	v_mul_f32_e32 v133, v85, v133
	s_nop 0
	v_cvt_pk_bf16_f32 v134, v134, v135
	v_add_f32_e32 v138, 1.0, v138
	v_rcp_f32_e32 v138, v138
	s_nop 0
	v_mul_f32_e32 v136, v136, v138
	v_mul_f32_e32 v138, 0xbfb8aa3b, v133
	v_exp_f32_e32 v138, v138
	s_nop 0
	v_add_f32_e32 v138, 1.0, v138
	v_rcp_f32_e32 v138, v138
	s_nop 0
	v_mul_f32_e32 v133, v133, v138
	s_nop 0
	v_cvt_pk_bf16_f32 v135, v136, v133
	ds_write_b64 v132, v[134:135] offset:8768
	v_mov_b32_e32 v133, v148
	v_mul_f32_e32 v134, v78, v133
	v_mul_f32_e32 v135, 0xbfb8aa3b, v134
	v_exp_f32_e32 v135, v135
	s_nop 0
	v_add_f32_e32 v135, 1.0, v135
	v_rcp_f32_e32 v135, v135
	s_nop 0
	v_mul_f32_e32 v134, v134, v135
	v_mul_f32_e32 v135, v79, v133
	v_mul_f32_e32 v136, 0xbfb8aa3b, v135
	v_exp_f32_e32 v136, v136
	s_nop 0
	v_add_f32_e32 v136, 1.0, v136
	v_rcp_f32_e32 v136, v136
	s_nop 0
	v_mul_f32_e32 v135, v135, v136
	v_mul_f32_e32 v136, v80, v133
	v_mul_f32_e32 v138, 0xbfb8aa3b, v136
	v_exp_f32_e32 v138, v138
	v_mul_f32_e32 v133, v81, v133
	s_nop 0
	v_cvt_pk_bf16_f32 v134, v134, v135
	v_add_f32_e32 v138, 1.0, v138
	v_rcp_f32_e32 v138, v138
	s_nop 0
	v_mul_f32_e32 v136, v136, v138
	v_mul_f32_e32 v138, 0xbfb8aa3b, v133
	v_exp_f32_e32 v138, v138
	s_nop 0
	v_add_f32_e32 v138, 1.0, v138
	v_rcp_f32_e32 v138, v138
	s_nop 0
	v_mul_f32_e32 v133, v133, v138
	s_nop 0
	v_cvt_pk_bf16_f32 v135, v136, v133
	ds_write_b64 v131, v[134:135] offset:96
	v_mov_b32_e32 v133, v149
	v_mul_f32_e32 v134, v70, v133
	v_mul_f32_e32 v135, 0xbfb8aa3b, v134
	v_exp_f32_e32 v135, v135
	s_nop 0
	v_add_f32_e32 v135, 1.0, v135
	v_rcp_f32_e32 v135, v135
	s_nop 0
	v_mul_f32_e32 v134, v134, v135
	v_mul_f32_e32 v135, v71, v133
	v_mul_f32_e32 v136, 0xbfb8aa3b, v135
	v_exp_f32_e32 v136, v136
	s_nop 0
	v_add_f32_e32 v136, 1.0, v136
	v_rcp_f32_e32 v136, v136
	s_nop 0
	v_mul_f32_e32 v135, v135, v136
	v_mul_f32_e32 v136, v72, v133
	v_mul_f32_e32 v138, 0xbfb8aa3b, v136
	v_exp_f32_e32 v138, v138
	v_mul_f32_e32 v133, v73, v133
	s_nop 0
	v_cvt_pk_bf16_f32 v134, v134, v135
	v_add_f32_e32 v138, 1.0, v138
	v_rcp_f32_e32 v138, v138
	s_nop 0
	v_mul_f32_e32 v136, v136, v138
	v_mul_f32_e32 v138, 0xbfb8aa3b, v133
	v_exp_f32_e32 v138, v138
	s_nop 0
	v_add_f32_e32 v138, 1.0, v138
	v_rcp_f32_e32 v138, v138
	s_nop 0
	v_mul_f32_e32 v133, v133, v138
	s_nop 0
	v_cvt_pk_bf16_f32 v135, v136, v133
	ds_write_b64 v131, v[134:135] offset:8800
	v_mov_b32_e32 v133, v150
	v_mul_f32_e32 v134, v74, v133
	v_mul_f32_e32 v135, 0xbfb8aa3b, v134
	v_exp_f32_e32 v135, v135
	s_nop 0
	v_add_f32_e32 v135, 1.0, v135
	v_rcp_f32_e32 v135, v135
	s_nop 0
	v_mul_f32_e32 v134, v134, v135
	v_mul_f32_e32 v135, v75, v133
	v_mul_f32_e32 v136, 0xbfb8aa3b, v135
	v_exp_f32_e32 v136, v136
	s_nop 0
	v_add_f32_e32 v136, 1.0, v136
	v_rcp_f32_e32 v136, v136
	s_nop 0
	v_mul_f32_e32 v135, v135, v136
	v_mul_f32_e32 v136, v76, v133
	v_mul_f32_e32 v138, 0xbfb8aa3b, v136
	v_exp_f32_e32 v138, v138
	v_mul_f32_e32 v133, v77, v133
	s_nop 0
	v_cvt_pk_bf16_f32 v134, v134, v135
	v_add_f32_e32 v138, 1.0, v138
	v_rcp_f32_e32 v138, v138
	s_nop 0
	v_mul_f32_e32 v136, v136, v138
	v_mul_f32_e32 v138, 0xbfb8aa3b, v133
	v_exp_f32_e32 v138, v138
	s_nop 0
	v_add_f32_e32 v138, 1.0, v138
	v_rcp_f32_e32 v138, v138
	s_nop 0
	v_mul_f32_e32 v133, v133, v138
	s_nop 0
	v_cvt_pk_bf16_f32 v135, v136, v133
	ds_write_b64 v130, v[134:135] offset:61024
	v_mov_b32_e32 v133, v151
	v_mul_f32_e32 v134, v62, v133
	v_mul_f32_e32 v135, 0xbfb8aa3b, v134
	v_exp_f32_e32 v135, v135
	s_nop 0
	v_add_f32_e32 v135, 1.0, v135
	v_rcp_f32_e32 v135, v135
	s_nop 0
	v_mul_f32_e32 v134, v134, v135
	v_mul_f32_e32 v135, v63, v133
	v_mul_f32_e32 v136, 0xbfb8aa3b, v135
	v_exp_f32_e32 v136, v136
	s_nop 0
	v_add_f32_e32 v136, 1.0, v136
	v_rcp_f32_e32 v136, v136
	s_nop 0
	v_mul_f32_e32 v135, v135, v136
	v_mul_f32_e32 v136, v64, v133
	v_mul_f32_e32 v138, 0xbfb8aa3b, v136
	v_exp_f32_e32 v138, v138
	v_mul_f32_e32 v133, v65, v133
	s_nop 0
	v_cvt_pk_bf16_f32 v134, v134, v135
	v_add_f32_e32 v138, 1.0, v138
	v_rcp_f32_e32 v138, v138
	s_nop 0
	v_mul_f32_e32 v136, v136, v138
	v_mul_f32_e32 v138, 0xbfb8aa3b, v133
	v_exp_f32_e32 v138, v138
	s_nop 0
	v_add_f32_e32 v138, 1.0, v138
	v_rcp_f32_e32 v138, v138
	s_nop 0
	v_mul_f32_e32 v133, v133, v138
	s_nop 0
	v_cvt_pk_bf16_f32 v135, v136, v133
	ds_write_b64 v132, v[134:135] offset:8800
	v_mov_b32_e32 v133, v148
	v_mul_f32_e32 v134, v66, v133
	v_mul_f32_e32 v135, 0xbfb8aa3b, v134
	v_exp_f32_e32 v135, v135
	s_nop 0
	v_add_f32_e32 v135, 1.0, v135
	v_rcp_f32_e32 v135, v135
	s_nop 0
	v_mul_f32_e32 v134, v134, v135
	v_mul_f32_e32 v135, v67, v133
	v_mul_f32_e32 v136, 0xbfb8aa3b, v135
	v_exp_f32_e32 v136, v136
	s_nop 0
	v_add_f32_e32 v136, 1.0, v136
	v_rcp_f32_e32 v136, v136
	s_nop 0
	v_mul_f32_e32 v135, v135, v136
	v_mul_f32_e32 v136, v68, v133
	v_mul_f32_e32 v138, 0xbfb8aa3b, v136
	v_exp_f32_e32 v138, v138
	v_mul_f32_e32 v133, v69, v133
	s_nop 0
	v_cvt_pk_bf16_f32 v134, v134, v135
	v_add_f32_e32 v138, 1.0, v138
	v_rcp_f32_e32 v138, v138
	s_nop 0
	v_mul_f32_e32 v136, v136, v138
	v_mul_f32_e32 v138, 0xbfb8aa3b, v133
	v_exp_f32_e32 v138, v138
	s_nop 0
	v_add_f32_e32 v138, 1.0, v138
	v_rcp_f32_e32 v138, v138
	s_nop 0
	v_mul_f32_e32 v133, v133, v138
	s_nop 0
	v_cvt_pk_bf16_f32 v135, v136, v133
	ds_write_b64 v131, v[134:135] offset:256
	v_mov_b32_e32 v133, v149
	v_mul_f32_e32 v134, v54, v133
	v_mul_f32_e32 v135, 0xbfb8aa3b, v134
; __device__ __forceinline__ float siluf(float x) { return x * __builtin_amdgcn_rcpf(1.f + __expf(-x)); }
; #define STAGE_TILE_F(XFORM) do { SW_BEGIN f32x4 v = acc[ai][bj][m][n2]; XFORM; \
;     *(u32x2*)(smem + mrow * SPITCH + nc0 * 2) = u32x2{cvtpk_t(v[0], v[1]), cvtpk_t(v[2], v[3])}; LOOP_END __syncthreads(); } while (0)
; template <int kind> __device__ __forceinline__ void gemm_phase_n(const Params& P, int layer, int b, const int wv) {
;     ...
;                 } else if (pn < 12) {
;                     STAGE_TILE_F(const float r = rs_lds[mrow]; v[0] = siluf(v[0] * r); v[1] = siluf(v[1] * r); v[2] = siluf(v[2] * r); v[3] = siluf(v[3] * r));
;                     u16* dst = (u16*)(ws + O_SG) + (size_t)t0 * 2048 + (pn - 4) * 256;
;                     DRAIN_BEGIN *(u32x4*)(dst + (size_t)row * 2048 + chunk * 8) = w; LOOP_END
	v_exp_f32_e32 v135, v135
	s_nop 0
	v_add_f32_e32 v135, 1.0, v135
	v_rcp_f32_e32 v135, v135
	s_nop 0
	v_mul_f32_e32 v134, v134, v135
	v_mul_f32_e32 v135, v55, v133
	v_mul_f32_e32 v136, 0xbfb8aa3b, v135
	v_exp_f32_e32 v136, v136
	s_nop 0
	v_add_f32_e32 v136, 1.0, v136
	v_rcp_f32_e32 v136, v136
	s_nop 0
	v_mul_f32_e32 v135, v135, v136
	v_mul_f32_e32 v136, v56, v133
	v_mul_f32_e32 v138, 0xbfb8aa3b, v136
	v_exp_f32_e32 v138, v138
	v_mul_f32_e32 v133, v57, v133
	s_nop 0
	v_cvt_pk_bf16_f32 v134, v134, v135
	v_add_f32_e32 v138, 1.0, v138
	v_rcp_f32_e32 v138, v138
	s_nop 0
	v_mul_f32_e32 v136, v136, v138
	v_mul_f32_e32 v138, 0xbfb8aa3b, v133
	v_exp_f32_e32 v138, v138
	s_nop 0
	v_add_f32_e32 v138, 1.0, v138
	v_rcp_f32_e32 v138, v138
	s_nop 0
	v_mul_f32_e32 v133, v133, v138
	s_nop 0
	v_cvt_pk_bf16_f32 v135, v136, v133
	ds_write_b64 v131, v[134:135] offset:8960
	v_mov_b32_e32 v133, v150
	v_mul_f32_e32 v134, v58, v133
	v_mul_f32_e32 v135, 0xbfb8aa3b, v134
	v_exp_f32_e32 v135, v135
	s_nop 0
	v_add_f32_e32 v135, 1.0, v135
	v_rcp_f32_e32 v135, v135
	s_nop 0
	v_mul_f32_e32 v134, v134, v135
	v_mul_f32_e32 v135, v59, v133
	v_mul_f32_e32 v136, 0xbfb8aa3b, v135
	v_exp_f32_e32 v136, v136
	s_nop 0
	v_add_f32_e32 v136, 1.0, v136
	v_rcp_f32_e32 v136, v136
	s_nop 0
	v_mul_f32_e32 v135, v135, v136
	v_mul_f32_e32 v136, v60, v133
	v_mul_f32_e32 v138, 0xbfb8aa3b, v136
	v_exp_f32_e32 v138, v138
	v_mul_f32_e32 v133, v61, v133
	s_nop 0
	v_cvt_pk_bf16_f32 v134, v134, v135
	v_add_f32_e32 v138, 1.0, v138
	v_rcp_f32_e32 v138, v138
	s_nop 0
	v_mul_f32_e32 v136, v136, v138
	v_mul_f32_e32 v138, 0xbfb8aa3b, v133
	v_exp_f32_e32 v138, v138
	s_nop 0
	v_add_f32_e32 v138, 1.0, v138
	v_rcp_f32_e32 v138, v138
	s_nop 0
	v_mul_f32_e32 v133, v133, v138
	s_nop 0
	v_cvt_pk_bf16_f32 v135, v136, v133
	ds_write_b64 v130, v[134:135] offset:61184
	v_mov_b32_e32 v133, v151
	v_mul_f32_e32 v134, v50, v133
	v_mul_f32_e32 v135, 0xbfb8aa3b, v134
	v_exp_f32_e32 v135, v135
	s_nop 0
	v_add_f32_e32 v135, 1.0, v135
	v_rcp_f32_e32 v135, v135
	s_nop 0
	v_mul_f32_e32 v134, v134, v135
	v_mul_f32_e32 v135, v51, v133
	v_mul_f32_e32 v136, 0xbfb8aa3b, v135
	v_exp_f32_e32 v136, v136
	s_nop 0
	v_add_f32_e32 v136, 1.0, v136
	v_rcp_f32_e32 v136, v136
	s_nop 0
	v_mul_f32_e32 v135, v135, v136
	v_mul_f32_e32 v136, v52, v133
	v_mul_f32_e32 v138, 0xbfb8aa3b, v136
	v_exp_f32_e32 v138, v138
	v_mul_f32_e32 v133, v53, v133
	s_nop 0
	v_cvt_pk_bf16_f32 v134, v134, v135
	v_add_f32_e32 v138, 1.0, v138
	v_rcp_f32_e32 v138, v138
	s_nop 0
	v_mul_f32_e32 v136, v136, v138
	v_mul_f32_e32 v138, 0xbfb8aa3b, v133
	v_exp_f32_e32 v138, v138
	s_nop 0
	v_add_f32_e32 v138, 1.0, v138
	v_rcp_f32_e32 v138, v138
	s_nop 0
	v_mul_f32_e32 v133, v133, v138
	s_nop 0
	v_cvt_pk_bf16_f32 v135, v136, v133
	ds_write_b64 v132, v[134:135] offset:8960
	v_mov_b32_e32 v133, v148
	v_mul_f32_e32 v134, v46, v133
	v_mul_f32_e32 v135, 0xbfb8aa3b, v134
	v_exp_f32_e32 v135, v135
	s_nop 0
	v_add_f32_e32 v135, 1.0, v135
	v_rcp_f32_e32 v135, v135
	s_nop 0
	v_mul_f32_e32 v134, v134, v135
	v_mul_f32_e32 v135, v47, v133
	v_mul_f32_e32 v136, 0xbfb8aa3b, v135
	v_exp_f32_e32 v136, v136
	s_nop 0
	v_add_f32_e32 v136, 1.0, v136
	v_rcp_f32_e32 v136, v136
	s_nop 0
	v_mul_f32_e32 v135, v135, v136
	v_mul_f32_e32 v136, v48, v133
	v_mul_f32_e32 v138, 0xbfb8aa3b, v136
	v_exp_f32_e32 v138, v138
	v_mul_f32_e32 v133, v49, v133
	s_nop 0
	v_cvt_pk_bf16_f32 v134, v134, v135
	v_add_f32_e32 v138, 1.0, v138
	v_rcp_f32_e32 v138, v138
	s_nop 0
	v_mul_f32_e32 v136, v136, v138
	v_mul_f32_e32 v138, 0xbfb8aa3b, v133
	v_exp_f32_e32 v138, v138
	s_nop 0
	v_add_f32_e32 v138, 1.0, v138
	v_rcp_f32_e32 v138, v138
	s_nop 0
	v_mul_f32_e32 v133, v133, v138
	s_nop 0
	v_cvt_pk_bf16_f32 v135, v136, v133
	ds_write_b64 v131, v[134:135] offset:288
	v_mov_b32_e32 v133, v149
	v_mul_f32_e32 v134, v38, v133
	v_mul_f32_e32 v135, 0xbfb8aa3b, v134
	v_exp_f32_e32 v135, v135
	s_nop 0
	v_add_f32_e32 v135, 1.0, v135
	v_rcp_f32_e32 v135, v135
	s_nop 0
	v_mul_f32_e32 v134, v134, v135
	v_mul_f32_e32 v135, v39, v133
	v_mul_f32_e32 v136, 0xbfb8aa3b, v135
	v_exp_f32_e32 v136, v136
	s_nop 0
	v_add_f32_e32 v136, 1.0, v136
	v_rcp_f32_e32 v136, v136
	s_nop 0
	v_mul_f32_e32 v135, v135, v136
	v_mul_f32_e32 v136, v40, v133
	v_mul_f32_e32 v138, 0xbfb8aa3b, v136
	v_exp_f32_e32 v138, v138
	v_mul_f32_e32 v133, v41, v133
	s_nop 0
	v_cvt_pk_bf16_f32 v134, v134, v135
	v_add_f32_e32 v138, 1.0, v138
	v_rcp_f32_e32 v138, v138
	s_nop 0
	v_mul_f32_e32 v136, v136, v138
	v_mul_f32_e32 v138, 0xbfb8aa3b, v133
	v_exp_f32_e32 v138, v138
	s_nop 0
	v_add_f32_e32 v138, 1.0, v138
	v_rcp_f32_e32 v138, v138
	s_nop 0
	v_mul_f32_e32 v133, v133, v138
	s_nop 0
	v_cvt_pk_bf16_f32 v135, v136, v133
	ds_write_b64 v131, v[134:135] offset:8992
	v_mov_b32_e32 v133, v150
	v_mul_f32_e32 v134, v42, v133
	v_mul_f32_e32 v135, 0xbfb8aa3b, v134
	v_exp_f32_e32 v135, v135
	s_nop 0
	v_add_f32_e32 v135, 1.0, v135
	v_rcp_f32_e32 v135, v135
	s_nop 0
	v_mul_f32_e32 v134, v134, v135
	v_mul_f32_e32 v135, v43, v133
	v_mul_f32_e32 v136, 0xbfb8aa3b, v135
	v_exp_f32_e32 v136, v136
	s_nop 0
	v_add_f32_e32 v136, 1.0, v136
	v_rcp_f32_e32 v136, v136
	s_nop 0
	v_mul_f32_e32 v135, v135, v136
	v_mul_f32_e32 v136, v44, v133
	v_mul_f32_e32 v138, 0xbfb8aa3b, v136
	v_exp_f32_e32 v138, v138
	v_mul_f32_e32 v133, v45, v133
	s_nop 0
	v_cvt_pk_bf16_f32 v134, v134, v135
	v_add_f32_e32 v138, 1.0, v138
	v_rcp_f32_e32 v138, v138
	s_nop 0
	v_mul_f32_e32 v136, v136, v138
	v_mul_f32_e32 v138, 0xbfb8aa3b, v133
	v_exp_f32_e32 v138, v138
	s_nop 0
	v_add_f32_e32 v138, 1.0, v138
	v_rcp_f32_e32 v138, v138
	s_nop 0
	v_mul_f32_e32 v133, v133, v138
	s_nop 0
	v_cvt_pk_bf16_f32 v135, v136, v133
	ds_write_b64 v130, v[134:135] offset:61216
; __device__ __forceinline__ float siluf(float x) { return x * __builtin_amdgcn_rcpf(1.f + __expf(-x)); }
; #define STAGE_TILE_F(XFORM) do { SW_BEGIN f32x4 v = acc[ai][bj][m][n2]; XFORM; \
;     *(u32x2*)(smem + mrow * SPITCH + nc0 * 2) = u32x2{cvtpk_t(v[0], v[1]), cvtpk_t(v[2], v[3])}; LOOP_END __syncthreads(); } while (0)
; template <int kind> __device__ __forceinline__ void gemm_phase_n(const Params& P, int layer, int b, const int wv) {
;     ...
;                 } else if (pn < 12) {
;                     STAGE_TILE_F(const float r = rs_lds[mrow]; v[0] = siluf(v[0] * r); v[1] = siluf(v[1] * r); v[2] = siluf(v[2] * r); v[3] = siluf(v[3] * r));
;                     u16* dst = (u16*)(ws + O_SG) + (size_t)t0 * 2048 + (pn - 4) * 256;
;                     DRAIN_BEGIN *(u32x4*)(dst + (size_t)row * 2048 + chunk * 8) = w; LOOP_END
	v_mov_b32_e32 v133, v151
	v_mul_f32_e32 v134, v34, v133
	v_mul_f32_e32 v135, 0xbfb8aa3b, v134
	v_exp_f32_e32 v135, v135
	s_nop 0
	v_add_f32_e32 v135, 1.0, v135
	v_rcp_f32_e32 v135, v135
	s_nop 0
	v_mul_f32_e32 v134, v134, v135
	v_mul_f32_e32 v135, v35, v133
	v_mul_f32_e32 v136, 0xbfb8aa3b, v135
	v_exp_f32_e32 v136, v136
	s_nop 0
	v_add_f32_e32 v136, 1.0, v136
	v_rcp_f32_e32 v136, v136
	s_nop 0
	v_mul_f32_e32 v135, v135, v136
	v_mul_f32_e32 v136, v36, v133
	v_mul_f32_e32 v138, 0xbfb8aa3b, v136
	v_exp_f32_e32 v138, v138
	v_mul_f32_e32 v133, v37, v133
	s_nop 0
	v_cvt_pk_bf16_f32 v134, v134, v135
	v_add_f32_e32 v138, 1.0, v138
	v_rcp_f32_e32 v138, v138
	s_nop 0
	v_mul_f32_e32 v136, v136, v138
	v_mul_f32_e32 v138, 0xbfb8aa3b, v133
	v_exp_f32_e32 v138, v138
	s_nop 0
	v_add_f32_e32 v138, 1.0, v138
	v_rcp_f32_e32 v138, v138
	s_nop 0
	v_mul_f32_e32 v133, v133, v138
	s_nop 0
	v_cvt_pk_bf16_f32 v135, v136, v133
	ds_write_b64 v132, v[134:135] offset:8992
	v_mov_b32_e32 v133, v148
	v_mul_f32_e32 v134, v30, v133
	v_mul_f32_e32 v135, 0xbfb8aa3b, v134
	v_exp_f32_e32 v135, v135
	s_nop 0
	v_add_f32_e32 v135, 1.0, v135
	v_rcp_f32_e32 v135, v135
	s_nop 0
	v_mul_f32_e32 v134, v134, v135
	v_mul_f32_e32 v135, v31, v133
	v_mul_f32_e32 v136, 0xbfb8aa3b, v135
	v_exp_f32_e32 v136, v136
	s_nop 0
	v_add_f32_e32 v136, 1.0, v136
	v_rcp_f32_e32 v136, v136
	s_nop 0
	v_mul_f32_e32 v135, v135, v136
	v_mul_f32_e32 v136, v32, v133
	v_mul_f32_e32 v138, 0xbfb8aa3b, v136
	v_exp_f32_e32 v138, v138
	v_mul_f32_e32 v133, v33, v133
	s_nop 0
	v_cvt_pk_bf16_f32 v134, v134, v135
	v_add_f32_e32 v138, 1.0, v138
	v_rcp_f32_e32 v138, v138
	s_nop 0
	v_mul_f32_e32 v136, v136, v138
	v_mul_f32_e32 v138, 0xbfb8aa3b, v133
	v_exp_f32_e32 v138, v138
	s_nop 0
	v_add_f32_e32 v138, 1.0, v138
	v_rcp_f32_e32 v138, v138
	s_nop 0
	v_mul_f32_e32 v133, v133, v138
	s_nop 0
	v_cvt_pk_bf16_f32 v135, v136, v133
	ds_write_b64 v131, v[134:135] offset:320
	v_mov_b32_e32 v133, v149
	v_mul_f32_e32 v134, v22, v133
	v_mul_f32_e32 v135, 0xbfb8aa3b, v134
	v_exp_f32_e32 v135, v135
	s_nop 0
	v_add_f32_e32 v135, 1.0, v135
	v_rcp_f32_e32 v135, v135
	s_nop 0
	v_mul_f32_e32 v134, v134, v135
	v_mul_f32_e32 v135, v23, v133
	v_mul_f32_e32 v136, 0xbfb8aa3b, v135
	v_exp_f32_e32 v136, v136
	s_nop 0
	v_add_f32_e32 v136, 1.0, v136
	v_rcp_f32_e32 v136, v136
	s_nop 0
	v_mul_f32_e32 v135, v135, v136
	v_mul_f32_e32 v136, v24, v133
	v_mul_f32_e32 v138, 0xbfb8aa3b, v136
	v_exp_f32_e32 v138, v138
	v_mul_f32_e32 v133, v25, v133
	s_nop 0
	v_cvt_pk_bf16_f32 v134, v134, v135
	v_add_f32_e32 v138, 1.0, v138
	v_rcp_f32_e32 v138, v138
	s_nop 0
	v_mul_f32_e32 v136, v136, v138
	v_mul_f32_e32 v138, 0xbfb8aa3b, v133
	v_exp_f32_e32 v138, v138
	s_nop 0
	v_add_f32_e32 v138, 1.0, v138
	v_rcp_f32_e32 v138, v138
	s_nop 0
	v_mul_f32_e32 v133, v133, v138
	s_nop 0
	v_cvt_pk_bf16_f32 v135, v136, v133
	ds_write_b64 v131, v[134:135] offset:9024
	v_mov_b32_e32 v133, v150
	v_mul_f32_e32 v134, v26, v133
	v_mul_f32_e32 v135, 0xbfb8aa3b, v134
	v_exp_f32_e32 v135, v135
	s_nop 0
	v_add_f32_e32 v135, 1.0, v135
	v_rcp_f32_e32 v135, v135
	s_nop 0
	v_mul_f32_e32 v134, v134, v135
	v_mul_f32_e32 v135, v27, v133
	v_mul_f32_e32 v136, 0xbfb8aa3b, v135
	v_exp_f32_e32 v136, v136
	s_nop 0
	v_add_f32_e32 v136, 1.0, v136
	v_rcp_f32_e32 v136, v136
	s_nop 0
	v_mul_f32_e32 v135, v135, v136
	v_mul_f32_e32 v136, v28, v133
	v_mul_f32_e32 v138, 0xbfb8aa3b, v136
	v_exp_f32_e32 v138, v138
	v_mul_f32_e32 v133, v29, v133
	s_nop 0
	v_cvt_pk_bf16_f32 v134, v134, v135
	v_add_f32_e32 v138, 1.0, v138
	v_rcp_f32_e32 v138, v138
	s_nop 0
	v_mul_f32_e32 v136, v136, v138
	v_mul_f32_e32 v138, 0xbfb8aa3b, v133
	v_exp_f32_e32 v138, v138
	s_nop 0
	v_add_f32_e32 v138, 1.0, v138
	v_rcp_f32_e32 v138, v138
	s_nop 0
	v_mul_f32_e32 v133, v133, v138
	s_nop 0
	v_cvt_pk_bf16_f32 v135, v136, v133
	ds_write_b64 v130, v[134:135] offset:61248
	v_mov_b32_e32 v133, v151
	v_mul_f32_e32 v134, v18, v133
	v_mul_f32_e32 v135, 0xbfb8aa3b, v134
	v_exp_f32_e32 v135, v135
	s_nop 0
	v_add_f32_e32 v135, 1.0, v135
	v_rcp_f32_e32 v135, v135
	s_nop 0
	v_mul_f32_e32 v134, v134, v135
	v_mul_f32_e32 v135, v19, v133
	v_mul_f32_e32 v136, 0xbfb8aa3b, v135
	v_exp_f32_e32 v136, v136
	s_nop 0
	v_add_f32_e32 v136, 1.0, v136
	v_rcp_f32_e32 v136, v136
	s_nop 0
	v_mul_f32_e32 v135, v135, v136
	v_mul_f32_e32 v136, v20, v133
	v_mul_f32_e32 v138, 0xbfb8aa3b, v136
	v_exp_f32_e32 v138, v138
	v_mul_f32_e32 v133, v21, v133
	s_nop 0
	v_cvt_pk_bf16_f32 v134, v134, v135
	v_add_f32_e32 v138, 1.0, v138
	v_rcp_f32_e32 v138, v138
	s_nop 0
	v_mul_f32_e32 v136, v136, v138
	v_mul_f32_e32 v138, 0xbfb8aa3b, v133
; __device__ __forceinline__ float siluf(float x) { return x * __builtin_amdgcn_rcpf(1.f + __expf(-x)); }
; #define STAGE_TILE_F(XFORM) do { SW_BEGIN f32x4 v = acc[ai][bj][m][n2]; XFORM; \
;     *(u32x2*)(smem + mrow * SPITCH + nc0 * 2) = u32x2{cvtpk_t(v[0], v[1]), cvtpk_t(v[2], v[3])}; LOOP_END __syncthreads(); } while (0)
; template <int kind> __device__ __forceinline__ void gemm_phase_n(const Params& P, int layer, int b, const int wv) {
;     ...
;                 } else if (pn < 12) {
;                     STAGE_TILE_F(const float r = rs_lds[mrow]; v[0] = siluf(v[0] * r); v[1] = siluf(v[1] * r); v[2] = siluf(v[2] * r); v[3] = siluf(v[3] * r));
;                     u16* dst = (u16*)(ws + O_SG) + (size_t)t0 * 2048 + (pn - 4) * 256;
;                     DRAIN_BEGIN *(u32x4*)(dst + (size_t)row * 2048 + chunk * 8) = w; LOOP_END
	v_exp_f32_e32 v138, v138
	s_nop 0
	v_add_f32_e32 v138, 1.0, v138
	v_rcp_f32_e32 v138, v138
	s_nop 0
	v_mul_f32_e32 v133, v133, v138
	s_nop 0
	v_cvt_pk_bf16_f32 v135, v136, v133
	ds_write_b64 v132, v[134:135] offset:9024
	v_mov_b32_e32 v133, v148
	v_mul_f32_e32 v134, v14, v133
	v_mul_f32_e32 v135, 0xbfb8aa3b, v134
	v_exp_f32_e32 v135, v135
	s_nop 0
	v_add_f32_e32 v135, 1.0, v135
	v_rcp_f32_e32 v135, v135
	s_nop 0
	v_mul_f32_e32 v134, v134, v135
	v_mul_f32_e32 v135, v15, v133
	v_mul_f32_e32 v136, 0xbfb8aa3b, v135
	v_exp_f32_e32 v136, v136
	s_nop 0
	v_add_f32_e32 v136, 1.0, v136
	v_rcp_f32_e32 v136, v136
	s_nop 0
	v_mul_f32_e32 v135, v135, v136
	v_mul_f32_e32 v136, v16, v133
	v_mul_f32_e32 v138, 0xbfb8aa3b, v136
	v_exp_f32_e32 v138, v138
	v_mul_f32_e32 v133, v17, v133
	s_nop 0
	v_cvt_pk_bf16_f32 v134, v134, v135
	v_add_f32_e32 v138, 1.0, v138
	v_rcp_f32_e32 v138, v138
	s_nop 0
	v_mul_f32_e32 v136, v136, v138
	v_mul_f32_e32 v138, 0xbfb8aa3b, v133
	v_exp_f32_e32 v138, v138
	s_nop 0
	v_add_f32_e32 v138, 1.0, v138
	v_rcp_f32_e32 v138, v138
	s_nop 0
	v_mul_f32_e32 v133, v133, v138
	s_nop 0
	v_cvt_pk_bf16_f32 v135, v136, v133
	ds_write_b64 v131, v[134:135] offset:352
	v_mov_b32_e32 v133, v149
	v_mul_f32_e32 v134, v2, v133
	v_mul_f32_e32 v135, 0xbfb8aa3b, v134
	v_exp_f32_e32 v135, v135
	s_nop 0
	v_add_f32_e32 v135, 1.0, v135
	v_rcp_f32_e32 v135, v135
	s_nop 0
	v_mul_f32_e32 v134, v134, v135
	v_mul_f32_e32 v135, v3, v133
	v_mul_f32_e32 v136, 0xbfb8aa3b, v135
	v_exp_f32_e32 v136, v136
	s_nop 0
	v_add_f32_e32 v136, 1.0, v136
	v_rcp_f32_e32 v136, v136
	s_nop 0
	v_mul_f32_e32 v135, v135, v136
	v_mul_f32_e32 v136, v4, v133
	v_mul_f32_e32 v138, 0xbfb8aa3b, v136
	v_exp_f32_e32 v138, v138
	v_mul_f32_e32 v133, v5, v133
	s_nop 0
	v_cvt_pk_bf16_f32 v134, v134, v135
	v_add_f32_e32 v138, 1.0, v138
	v_rcp_f32_e32 v138, v138
	s_nop 0
	v_mul_f32_e32 v136, v136, v138
	v_mul_f32_e32 v138, 0xbfb8aa3b, v133
	v_exp_f32_e32 v138, v138
	s_nop 0
	v_add_f32_e32 v138, 1.0, v138
	v_rcp_f32_e32 v138, v138
	s_nop 0
	v_mul_f32_e32 v133, v133, v138
	s_nop 0
	v_cvt_pk_bf16_f32 v135, v136, v133
	ds_write_b64 v131, v[134:135] offset:9056
	v_mov_b32_e32 v131, v150
	v_mul_f32_e32 v133, v10, v131
	v_mul_f32_e32 v134, 0xbfb8aa3b, v133
	v_exp_f32_e32 v134, v134
	s_nop 0
	v_add_f32_e32 v134, 1.0, v134
	v_rcp_f32_e32 v134, v134
	s_nop 0
	v_mul_f32_e32 v133, v133, v134
	v_mul_f32_e32 v134, v11, v131
	v_mul_f32_e32 v135, 0xbfb8aa3b, v134
	v_exp_f32_e32 v135, v135
	s_nop 0
	v_add_f32_e32 v135, 1.0, v135
	v_rcp_f32_e32 v135, v135
	s_nop 0
	v_mul_f32_e32 v134, v134, v135
	v_mul_f32_e32 v135, v12, v131
	v_mul_f32_e32 v136, 0xbfb8aa3b, v135
	v_exp_f32_e32 v136, v136
	v_mul_f32_e32 v131, v13, v131
	s_nop 0
	v_cvt_pk_bf16_f32 v134, v133, v134
	v_add_f32_e32 v136, 1.0, v136
	v_rcp_f32_e32 v136, v136
	s_nop 0
	v_mul_f32_e32 v135, v135, v136
	v_mul_f32_e32 v136, 0xbfb8aa3b, v131
	v_exp_f32_e32 v136, v136
	s_nop 0
	v_add_f32_e32 v136, 1.0, v136
	v_rcp_f32_e32 v136, v136
	s_nop 0
	v_mul_f32_e32 v131, v131, v136
	s_nop 0
	v_cvt_pk_bf16_f32 v135, v135, v131
	ds_write_b64 v130, v[134:135] offset:61280
	v_mov_b32_e32 v0, v151
	v_mul_f32_e32 v130, v6, v0
	v_mul_f32_e32 v131, 0xbfb8aa3b, v130
	v_exp_f32_e32 v131, v131
	s_nop 0
	v_add_f32_e32 v131, 1.0, v131
	v_rcp_f32_e32 v131, v131
	s_nop 0
	v_mul_f32_e32 v130, v130, v131
	v_mul_f32_e32 v131, v7, v0
	v_mul_f32_e32 v133, 0xbfb8aa3b, v131
	v_exp_f32_e32 v133, v133
	s_nop 0
	v_add_f32_e32 v133, 1.0, v133
	v_rcp_f32_e32 v133, v133
	s_nop 0
	v_mul_f32_e32 v131, v131, v133
	v_mul_f32_e32 v133, v8, v0
	v_mul_f32_e32 v134, 0xbfb8aa3b, v133
	v_exp_f32_e32 v134, v134
	v_mul_f32_e32 v0, v9, v0
	s_nop 0
	v_cvt_pk_bf16_f32 v130, v130, v131
	v_add_f32_e32 v134, 1.0, v134
	v_rcp_f32_e32 v134, v134
	s_nop 0
	v_mul_f32_e32 v133, v133, v134
	v_mul_f32_e32 v134, 0xbfb8aa3b, v0
	v_exp_f32_e32 v134, v134
	s_nop 0
	v_add_f32_e32 v134, 1.0, v134
	v_rcp_f32_e32 v134, v134
	s_nop 0
	v_mul_f32_e32 v0, v0, v134
	s_nop 0
	v_cvt_pk_bf16_f32 v131, v133, v0
	ds_write_b64 v132, v[130:131] offset:9056
	v_ashrrev_i32_e32 v132, 5, v137
	v_ashrrev_i32_e32 v133, 31, v132
	v_lshlrev_b64 v[130:131], 12, v[132:133]
	v_lshlrev_b32_e32 v0, 4, v137
	v_lshl_add_u64 v[130:131], v[130:131], 0, s[2:3]
	s_lshl_b64 s[2:3], s[14:15], 1
	v_and_b32_e32 v0, 0x1f0, v0
	s_add_u32 s2, s21, s2
	v_or_b32_e32 v130, v130, v0
	s_addc_u32 s3, s22, s3
	v_lshl_add_u64 v[130:131], s[2:3], 0, v[130:131]
	s_movk_i32 s2, 0x220
	v_mul_lo_u32 v132, v132, s2
	v_add3_u32 v0, v132, v0, 0
	s_mov_b64 s[2:3], 0
	s_waitcnt vmcnt(0) lgkmcnt(0)
	s_barrier

; __device__ __forceinline__ float siluf(float x) { return x * __builtin_amdgcn_rcpf(1.f + __expf(-x)); }
; #define STAGE_TILE_F(XFORM) do { SW_BEGIN f32x4 v = acc[ai][bj][m][n2]; XFORM; \
;     *(u32x2*)(smem + mrow * SPITCH + nc0 * 2) = u32x2{cvtpk_t(v[0], v[1]), cvtpk_t(v[2], v[3])}; LOOP_END __syncthreads(); } while (0)
; template <int kind> __device__ __forceinline__ void gemm_phase_n(const Params& P, int layer, int b, const int wv) {
;     ...
;                 } else {
;                     STAGE_TILE_F(const float r = rs_lds[mrow]; v[0] = siluf(v[0] * r); v[1] = siluf(v[1] * r); v[2] = siluf(v[2] * r); v[3] = siluf(v[3] * r));
;                     u16* dst = (u16*)(ws + O_SG) + (size_t)t0 * 2048 + (pn - 16) * 256;
;                     DRAIN_BEGIN *(u32x4*)(dst + (size_t)row * 2048 + chunk * 8) = w; LOOP_END
.LBB0_719:
	s_or_b64 exec, exec, s[2:3]
	v_mov_b32_e32 v0, v1
	s_cmp_gt_i32 s34, 7
	v_mbcnt_lo_u32_b32 v0, -1, v0
	v_mbcnt_hi_u32_b32 v0, -1, v0
	v_or_b32_e32 v132, s57, v0
	s_mov_b64 s[2:3], -1
	v_ashrrev_i32_e32 v133, 8, v132
	v_bfe_u32 v136, v132, 6, 2
	v_and_b32_e32 v135, 15, v132
	v_bfe_u32 v134, v132, 4, 2
	s_cbranch_scc0 .LBB0_728
	s_and_b32 s2, s34, 0xffff
	s_cmp_lt_u32 s2, 16
	s_mov_b64 s[2:3], -1
	s_cbranch_scc1 .LBB0_724
	v_lshl_or_b32 v137, v136, 5, v135
	v_lshl_add_u32 v0, v137, 2, 0
	v_add_u32_e32 v0, 0x22000, v0
	ds_read_b32 v148, v0
	ds_read_b32 v149, v0 offset:64
	ds_read_b32 v150, v0 offset:512
	ds_read_b32 v151, v0 offset:576
	s_waitcnt lgkmcnt(0)
	v_mov_b32_e32 v138, v148
	v_lshlrev_b32_e32 v130, 7, v133
	v_lshl_add_u32 v131, v134, 3, 0
	v_mul_u32_u24_e32 v137, 0x220, v137
	v_add3_u32 v131, v131, v130, v137
	v_mul_f32_e32 v139, v122, v138
	v_mul_f32_e32 v140, 0xbfb8aa3b, v139
	v_exp_f32_e32 v140, v140
	s_lshl_b64 s[2:3], s[4:5], 12
	s_mov_b32 s15, s73
	v_add_f32_e32 v140, 1.0, v140
	v_rcp_f32_e32 v140, v140
	s_nop 0
	v_mul_f32_e32 v139, v139, v140
	v_mul_f32_e32 v140, v123, v138
	v_mul_f32_e32 v141, 0xbfb8aa3b, v140
	v_exp_f32_e32 v141, v141
	s_nop 0
	v_add_f32_e32 v141, 1.0, v141
	v_rcp_f32_e32 v141, v141
	s_nop 0
	v_mul_f32_e32 v140, v140, v141
	v_mul_f32_e32 v141, v124, v138
	v_mul_f32_e32 v142, 0xbfb8aa3b, v141
	v_exp_f32_e32 v142, v142
	v_mul_f32_e32 v138, v125, v138
	v_add_f32_e32 v142, 1.0, v142
	v_rcp_f32_e32 v142, v142
	s_nop 0
	v_mul_f32_e32 v141, v141, v142
	v_mul_f32_e32 v142, 0xbfb8aa3b, v138
	v_exp_f32_e32 v142, v142
	s_nop 0
	v_add_f32_e32 v142, 1.0, v142
	v_rcp_f32_e32 v142, v142
	s_nop 0
	v_mul_f32_e32 v142, v138, v142
	s_nop 0
	v_cvt_pk_bf16_f32 v138, v139, v140
	s_nop 0
	v_cvt_pk_bf16_f32 v139, v141, v142
	ds_write_b64 v131, v[138:139]
	v_mov_b32_e32 v130, v149
	v_mul_f32_e32 v137, v90, v130
	v_mul_f32_e32 v138, 0xbfb8aa3b, v137
	v_exp_f32_e32 v138, v138
	s_nop 0
	v_add_f32_e32 v138, 1.0, v138
	v_rcp_f32_e32 v138, v138
	s_nop 0
	v_mul_f32_e32 v137, v137, v138
	v_mul_f32_e32 v138, v91, v130
	v_mul_f32_e32 v139, 0xbfb8aa3b, v138
	v_exp_f32_e32 v139, v139
	s_nop 0
	v_add_f32_e32 v139, 1.0, v139
	v_rcp_f32_e32 v139, v139
	s_nop 0
	v_mul_f32_e32 v138, v138, v139
	v_mul_f32_e32 v139, v92, v130
	v_mul_f32_e32 v140, 0xbfb8aa3b, v139
	v_exp_f32_e32 v140, v140
	v_mul_f32_e32 v130, v93, v130
	s_nop 0
	v_cvt_pk_bf16_f32 v138, v137, v138
	v_add_f32_e32 v140, 1.0, v140
	v_rcp_f32_e32 v140, v140
	s_nop 0
	v_mul_f32_e32 v139, v139, v140
	v_mul_f32_e32 v140, 0xbfb8aa3b, v130
	v_exp_f32_e32 v140, v140
	s_nop 0
	v_add_f32_e32 v140, 1.0, v140
	v_rcp_f32_e32 v140, v140
	s_nop 0
	v_mul_f32_e32 v130, v130, v140
	s_nop 0
	v_cvt_pk_bf16_f32 v139, v139, v130
	ds_write_b64 v131, v[138:139] offset:8704
	v_mov_b32_e32 v137, v150
	v_add_u32_e32 v130, 0x2200, v131
	v_mul_f32_e32 v138, v58, v137
	v_mul_f32_e32 v139, 0xbfb8aa3b, v138
	v_exp_f32_e32 v139, v139
	s_nop 0
	v_add_f32_e32 v139, 1.0, v139
	v_rcp_f32_e32 v139, v139
	s_nop 0
	v_mul_f32_e32 v138, v138, v139
	v_mul_f32_e32 v139, v59, v137
	v_mul_f32_e32 v140, 0xbfb8aa3b, v139
	v_exp_f32_e32 v140, v140
	s_nop 0
	v_add_f32_e32 v140, 1.0, v140
	v_rcp_f32_e32 v140, v140
	s_nop 0
	v_mul_f32_e32 v139, v139, v140
	v_mul_f32_e32 v140, v60, v137
	v_mul_f32_e32 v141, 0xbfb8aa3b, v140
	v_exp_f32_e32 v141, v141
	v_mul_f32_e32 v137, v61, v137
	s_nop 0
	v_cvt_pk_bf16_f32 v138, v138, v139
	v_add_f32_e32 v141, 1.0, v141
	v_rcp_f32_e32 v141, v141
	s_nop 0
	v_mul_f32_e32 v140, v140, v141
	v_mul_f32_e32 v141, 0xbfb8aa3b, v137
	v_exp_f32_e32 v141, v141
	s_nop 0
	v_add_f32_e32 v141, 1.0, v141
	v_rcp_f32_e32 v141, v141
	s_nop 0
	v_mul_f32_e32 v137, v137, v141
	s_nop 0
	v_cvt_pk_bf16_f32 v139, v140, v137
	ds_write_b64 v130, v[138:139] offset:60928
	v_mov_b32_e32 v138, v151
	v_add_u32_e32 v137, 0xee00, v130
	v_mul_f32_e32 v139, v26, v138
	v_mul_f32_e32 v140, 0xbfb8aa3b, v139
	v_exp_f32_e32 v140, v140
	s_nop 0
	v_add_f32_e32 v140, 1.0, v140
	v_rcp_f32_e32 v140, v140
	s_nop 0
	v_mul_f32_e32 v139, v139, v140
	v_mul_f32_e32 v140, v27, v138
	v_mul_f32_e32 v141, 0xbfb8aa3b, v140
	v_exp_f32_e32 v141, v141
	s_nop 0
	v_add_f32_e32 v141, 1.0, v141
	v_rcp_f32_e32 v141, v141
	s_nop 0
	v_mul_f32_e32 v140, v140, v141
	v_mul_f32_e32 v141, v28, v138
	v_mul_f32_e32 v142, 0xbfb8aa3b, v141
	v_exp_f32_e32 v142, v142
	v_mul_f32_e32 v138, v29, v138
	v_add_f32_e32 v142, 1.0, v142
	v_rcp_f32_e32 v142, v142
	s_nop 0
	v_mul_f32_e32 v141, v141, v142
	v_mul_f32_e32 v142, 0xbfb8aa3b, v138
	v_exp_f32_e32 v142, v142
	s_nop 0
	v_add_f32_e32 v142, 1.0, v142
	v_rcp_f32_e32 v142, v142
	s_nop 0
	v_mul_f32_e32 v142, v138, v142
	s_nop 0
	v_cvt_pk_bf16_f32 v138, v139, v140
	s_nop 0
	v_cvt_pk_bf16_f32 v139, v141, v142
	ds_write_b64 v137, v[138:139] offset:8704
	v_mov_b32_e32 v138, v148
	v_mul_f32_e32 v139, v114, v138
	v_mul_f32_e32 v140, 0xbfb8aa3b, v139
	v_exp_f32_e32 v140, v140
	s_nop 0
	v_add_f32_e32 v140, 1.0, v140
	v_rcp_f32_e32 v140, v140
	s_nop 0
	v_mul_f32_e32 v139, v139, v140
	v_mul_f32_e32 v140, v115, v138
	v_mul_f32_e32 v141, 0xbfb8aa3b, v140
	v_exp_f32_e32 v141, v141
	s_nop 0
	v_add_f32_e32 v141, 1.0, v141
	v_rcp_f32_e32 v141, v141
	s_nop 0
	v_mul_f32_e32 v140, v140, v141
	v_mul_f32_e32 v141, v116, v138
	v_mul_f32_e32 v142, 0xbfb8aa3b, v141
	v_exp_f32_e32 v142, v142
	v_mul_f32_e32 v138, v117, v138
	v_add_f32_e32 v142, 1.0, v142
	v_rcp_f32_e32 v142, v142
	s_nop 0
	v_mul_f32_e32 v141, v141, v142
	v_mul_f32_e32 v142, 0xbfb8aa3b, v138
	v_exp_f32_e32 v142, v142
	s_nop 0
	v_add_f32_e32 v142, 1.0, v142
	v_rcp_f32_e32 v142, v142
	s_nop 0
	v_mul_f32_e32 v142, v138, v142
	s_nop 0
	v_cvt_pk_bf16_f32 v138, v139, v140
	s_nop 0
; __device__ __forceinline__ float siluf(float x) { return x * __builtin_amdgcn_rcpf(1.f + __expf(-x)); }
; #define STAGE_TILE_F(XFORM) do { SW_BEGIN f32x4 v = acc[ai][bj][m][n2]; XFORM; \
;     *(u32x2*)(smem + mrow * SPITCH + nc0 * 2) = u32x2{cvtpk_t(v[0], v[1]), cvtpk_t(v[2], v[3])}; LOOP_END __syncthreads(); } while (0)
; template <int kind> __device__ __forceinline__ void gemm_phase_n(const Params& P, int layer, int b, const int wv) {
;     ...
;                 } else {
;                     STAGE_TILE_F(const float r = rs_lds[mrow]; v[0] = siluf(v[0] * r); v[1] = siluf(v[1] * r); v[2] = siluf(v[2] * r); v[3] = siluf(v[3] * r));
;                     u16* dst = (u16*)(ws + O_SG) + (size_t)t0 * 2048 + (pn - 16) * 256;
;                     DRAIN_BEGIN *(u32x4*)(dst + (size_t)row * 2048 + chunk * 8) = w; LOOP_END
	v_cvt_pk_bf16_f32 v139, v141, v142
	ds_write_b64 v131, v[138:139] offset:32
	v_mov_b32_e32 v138, v149
	v_mul_f32_e32 v139, v82, v138
	v_mul_f32_e32 v140, 0xbfb8aa3b, v139
	v_exp_f32_e32 v140, v140
	s_nop 0
	v_add_f32_e32 v140, 1.0, v140
	v_rcp_f32_e32 v140, v140
	s_nop 0
	v_mul_f32_e32 v139, v139, v140
	v_mul_f32_e32 v140, v83, v138
	v_mul_f32_e32 v141, 0xbfb8aa3b, v140
	v_exp_f32_e32 v141, v141
	s_nop 0
	v_add_f32_e32 v141, 1.0, v141
	v_rcp_f32_e32 v141, v141
	s_nop 0
	v_mul_f32_e32 v140, v140, v141
	v_mul_f32_e32 v141, v84, v138
	v_mul_f32_e32 v142, 0xbfb8aa3b, v141
	v_exp_f32_e32 v142, v142
	v_mul_f32_e32 v138, v85, v138
	v_add_f32_e32 v142, 1.0, v142
	v_rcp_f32_e32 v142, v142
	s_nop 0
	v_mul_f32_e32 v141, v141, v142
	v_mul_f32_e32 v142, 0xbfb8aa3b, v138
	v_exp_f32_e32 v142, v142
	s_nop 0
	v_add_f32_e32 v142, 1.0, v142
	v_rcp_f32_e32 v142, v142
	s_nop 0
	v_mul_f32_e32 v142, v138, v142
	s_nop 0
	v_cvt_pk_bf16_f32 v138, v139, v140
	s_nop 0
	v_cvt_pk_bf16_f32 v139, v141, v142
	ds_write_b64 v131, v[138:139] offset:8736
	v_mov_b32_e32 v138, v150
	v_mul_f32_e32 v139, v50, v138
	v_mul_f32_e32 v140, 0xbfb8aa3b, v139
	v_exp_f32_e32 v140, v140
	s_nop 0
	v_add_f32_e32 v140, 1.0, v140
	v_rcp_f32_e32 v140, v140
	s_nop 0
	v_mul_f32_e32 v139, v139, v140
	v_mul_f32_e32 v140, v51, v138
	v_mul_f32_e32 v141, 0xbfb8aa3b, v140
	v_exp_f32_e32 v141, v141
	s_nop 0
	v_add_f32_e32 v141, 1.0, v141
	v_rcp_f32_e32 v141, v141
	s_nop 0
	v_mul_f32_e32 v140, v140, v141
	v_mul_f32_e32 v141, v52, v138
	v_mul_f32_e32 v142, 0xbfb8aa3b, v141
	v_exp_f32_e32 v142, v142
	v_mul_f32_e32 v138, v53, v138
	v_add_f32_e32 v142, 1.0, v142
	v_rcp_f32_e32 v142, v142
	s_nop 0
	v_mul_f32_e32 v141, v141, v142
	v_mul_f32_e32 v142, 0xbfb8aa3b, v138
	v_exp_f32_e32 v142, v142
	s_nop 0
	v_add_f32_e32 v142, 1.0, v142
	v_rcp_f32_e32 v142, v142
	s_nop 0
	v_mul_f32_e32 v142, v138, v142
	s_nop 0
	v_cvt_pk_bf16_f32 v138, v139, v140
	s_nop 0
	v_cvt_pk_bf16_f32 v139, v141, v142
	ds_write_b64 v130, v[138:139] offset:60960
	v_mov_b32_e32 v138, v151
	v_mul_f32_e32 v139, v18, v138
	v_mul_f32_e32 v140, 0xbfb8aa3b, v139
	v_exp_f32_e32 v140, v140
	s_nop 0
	v_add_f32_e32 v140, 1.0, v140
	v_rcp_f32_e32 v140, v140
	s_nop 0
	v_mul_f32_e32 v139, v139, v140
	v_mul_f32_e32 v140, v19, v138
	v_mul_f32_e32 v141, 0xbfb8aa3b, v140
	v_exp_f32_e32 v141, v141
	s_nop 0
	v_add_f32_e32 v141, 1.0, v141
	v_rcp_f32_e32 v141, v141
	s_nop 0
	v_mul_f32_e32 v140, v140, v141
	v_mul_f32_e32 v141, v20, v138
	v_mul_f32_e32 v142, 0xbfb8aa3b, v141
	v_exp_f32_e32 v142, v142
	v_mul_f32_e32 v138, v21, v138
	v_add_f32_e32 v142, 1.0, v142
	v_rcp_f32_e32 v142, v142
	s_nop 0
	v_mul_f32_e32 v141, v141, v142
	v_mul_f32_e32 v142, 0xbfb8aa3b, v138
	v_exp_f32_e32 v142, v142
	s_nop 0
	v_add_f32_e32 v142, 1.0, v142
	v_rcp_f32_e32 v142, v142
	s_nop 0
	v_mul_f32_e32 v142, v138, v142
	s_nop 0
	v_cvt_pk_bf16_f32 v138, v139, v140
	s_nop 0
	v_cvt_pk_bf16_f32 v139, v141, v142
	ds_write_b64 v137, v[138:139] offset:8736
	v_mov_b32_e32 v138, v148
	v_mul_f32_e32 v139, v102, v138
	v_mul_f32_e32 v140, 0xbfb8aa3b, v139
	v_exp_f32_e32 v140, v140
	s_nop 0
	v_add_f32_e32 v140, 1.0, v140
	v_rcp_f32_e32 v140, v140
	s_nop 0
	v_mul_f32_e32 v139, v139, v140
	v_mul_f32_e32 v140, v103, v138
	v_mul_f32_e32 v141, 0xbfb8aa3b, v140
	v_exp_f32_e32 v141, v141
	s_nop 0
	v_add_f32_e32 v141, 1.0, v141
	v_rcp_f32_e32 v141, v141
	s_nop 0
	v_mul_f32_e32 v140, v140, v141
	v_mul_f32_e32 v141, v104, v138
	v_mul_f32_e32 v142, 0xbfb8aa3b, v141
	v_exp_f32_e32 v142, v142
	v_mul_f32_e32 v138, v105, v138
	v_add_f32_e32 v142, 1.0, v142
	v_rcp_f32_e32 v142, v142
	s_nop 0
	v_mul_f32_e32 v141, v141, v142
	v_mul_f32_e32 v142, 0xbfb8aa3b, v138
	v_exp_f32_e32 v142, v142
	s_nop 0
	v_add_f32_e32 v142, 1.0, v142
	v_rcp_f32_e32 v142, v142
	s_nop 0
	v_mul_f32_e32 v142, v138, v142
	s_nop 0
	v_cvt_pk_bf16_f32 v138, v139, v140
	s_nop 0
	v_cvt_pk_bf16_f32 v139, v141, v142
	ds_write_b64 v131, v[138:139] offset:64
	v_mov_b32_e32 v138, v149
	v_mul_f32_e32 v139, v70, v138
	v_mul_f32_e32 v140, 0xbfb8aa3b, v139
	v_exp_f32_e32 v140, v140
	s_nop 0
	v_add_f32_e32 v140, 1.0, v140
	v_rcp_f32_e32 v140, v140
	s_nop 0
	v_mul_f32_e32 v139, v139, v140
	v_mul_f32_e32 v140, v71, v138
	v_mul_f32_e32 v141, 0xbfb8aa3b, v140
	v_exp_f32_e32 v141, v141
	s_nop 0
	v_add_f32_e32 v141, 1.0, v141
	v_rcp_f32_e32 v141, v141
	s_nop 0
	v_mul_f32_e32 v140, v140, v141
	v_mul_f32_e32 v141, v72, v138
	v_mul_f32_e32 v142, 0xbfb8aa3b, v141
	v_exp_f32_e32 v142, v142
	v_mul_f32_e32 v138, v73, v138
	v_add_f32_e32 v142, 1.0, v142
	v_rcp_f32_e32 v142, v142
	s_nop 0
	v_mul_f32_e32 v141, v141, v142
	v_mul_f32_e32 v142, 0xbfb8aa3b, v138
	v_exp_f32_e32 v142, v142
	s_nop 0
	v_add_f32_e32 v142, 1.0, v142
	v_rcp_f32_e32 v142, v142
	s_nop 0
	v_mul_f32_e32 v142, v138, v142
	s_nop 0
	v_cvt_pk_bf16_f32 v138, v139, v140
	s_nop 0
	v_cvt_pk_bf16_f32 v139, v141, v142
	ds_write_b64 v131, v[138:139] offset:8768
	v_mov_b32_e32 v138, v150
	v_mul_f32_e32 v139, v38, v138
	v_mul_f32_e32 v140, 0xbfb8aa3b, v139
	v_exp_f32_e32 v140, v140
	s_nop 0
	v_add_f32_e32 v140, 1.0, v140
	v_rcp_f32_e32 v140, v140
	s_nop 0
	v_mul_f32_e32 v139, v139, v140
	v_mul_f32_e32 v140, v39, v138
	v_mul_f32_e32 v141, 0xbfb8aa3b, v140
	v_exp_f32_e32 v141, v141
	s_nop 0
	v_add_f32_e32 v141, 1.0, v141
	v_rcp_f32_e32 v141, v141
	s_nop 0
	v_mul_f32_e32 v140, v140, v141
	v_mul_f32_e32 v141, v40, v138
	v_mul_f32_e32 v142, 0xbfb8aa3b, v141
	v_exp_f32_e32 v142, v142
	v_mul_f32_e32 v138, v41, v138
	v_add_f32_e32 v142, 1.0, v142
	v_rcp_f32_e32 v142, v142
	s_nop 0
	v_mul_f32_e32 v141, v141, v142
	v_mul_f32_e32 v142, 0xbfb8aa3b, v138
	v_exp_f32_e32 v142, v142
	s_nop 0
	v_add_f32_e32 v142, 1.0, v142
; __device__ __forceinline__ float siluf(float x) { return x * __builtin_amdgcn_rcpf(1.f + __expf(-x)); }
; #define STAGE_TILE_F(XFORM) do { SW_BEGIN f32x4 v = acc[ai][bj][m][n2]; XFORM; \
;     *(u32x2*)(smem + mrow * SPITCH + nc0 * 2) = u32x2{cvtpk_t(v[0], v[1]), cvtpk_t(v[2], v[3])}; LOOP_END __syncthreads(); } while (0)
; template <int kind> __device__ __forceinline__ void gemm_phase_n(const Params& P, int layer, int b, const int wv) {
;     ...
;                 } else {
;                     STAGE_TILE_F(const float r = rs_lds[mrow]; v[0] = siluf(v[0] * r); v[1] = siluf(v[1] * r); v[2] = siluf(v[2] * r); v[3] = siluf(v[3] * r));
;                     u16* dst = (u16*)(ws + O_SG) + (size_t)t0 * 2048 + (pn - 16) * 256;
;                     DRAIN_BEGIN *(u32x4*)(dst + (size_t)row * 2048 + chunk * 8) = w; LOOP_END
	v_rcp_f32_e32 v142, v142
	s_nop 0
	v_mul_f32_e32 v142, v138, v142
	s_nop 0
	v_cvt_pk_bf16_f32 v138, v139, v140
	s_nop 0
	v_cvt_pk_bf16_f32 v139, v141, v142
	ds_write_b64 v130, v[138:139] offset:60992
	v_mov_b32_e32 v138, v151
	v_mul_f32_e32 v139, v10, v138
	v_mul_f32_e32 v140, 0xbfb8aa3b, v139
	v_exp_f32_e32 v140, v140
	s_nop 0
	v_add_f32_e32 v140, 1.0, v140
	v_rcp_f32_e32 v140, v140
	s_nop 0
	v_mul_f32_e32 v139, v139, v140
	v_mul_f32_e32 v140, v11, v138
	v_mul_f32_e32 v141, 0xbfb8aa3b, v140
	v_exp_f32_e32 v141, v141
	s_nop 0
	v_add_f32_e32 v141, 1.0, v141
	v_rcp_f32_e32 v141, v141
	s_nop 0
	v_mul_f32_e32 v140, v140, v141
	v_mul_f32_e32 v141, v12, v138
	v_mul_f32_e32 v142, 0xbfb8aa3b, v141
	v_exp_f32_e32 v142, v142
	v_mul_f32_e32 v138, v13, v138
	v_add_f32_e32 v142, 1.0, v142
	v_rcp_f32_e32 v142, v142
	s_nop 0
	v_mul_f32_e32 v141, v141, v142
	v_mul_f32_e32 v142, 0xbfb8aa3b, v138
	v_exp_f32_e32 v142, v142
	s_nop 0
	v_add_f32_e32 v142, 1.0, v142
	v_rcp_f32_e32 v142, v142
	s_nop 0
	v_mul_f32_e32 v142, v138, v142
	s_nop 0
	v_cvt_pk_bf16_f32 v138, v139, v140
	s_nop 0
	v_cvt_pk_bf16_f32 v139, v141, v142
	ds_write_b64 v137, v[138:139] offset:8768
	v_mov_b32_e32 v138, v148
	v_mul_f32_e32 v139, v98, v138
	v_mul_f32_e32 v140, 0xbfb8aa3b, v139
	v_exp_f32_e32 v140, v140
	s_nop 0
	v_add_f32_e32 v140, 1.0, v140
	v_rcp_f32_e32 v140, v140
	s_nop 0
	v_mul_f32_e32 v139, v139, v140
	v_mul_f32_e32 v140, v99, v138
	v_mul_f32_e32 v141, 0xbfb8aa3b, v140
	v_exp_f32_e32 v141, v141
	s_nop 0
	v_add_f32_e32 v141, 1.0, v141
	v_rcp_f32_e32 v141, v141
	s_nop 0
	v_mul_f32_e32 v140, v140, v141
	v_mul_f32_e32 v141, v100, v138
	v_mul_f32_e32 v142, 0xbfb8aa3b, v141
	v_exp_f32_e32 v142, v142
	v_mul_f32_e32 v138, v101, v138
	v_add_f32_e32 v142, 1.0, v142
	v_rcp_f32_e32 v142, v142
	s_nop 0
	v_mul_f32_e32 v141, v141, v142
	v_mul_f32_e32 v142, 0xbfb8aa3b, v138
	v_exp_f32_e32 v142, v142
	s_nop 0
	v_add_f32_e32 v142, 1.0, v142
	v_rcp_f32_e32 v142, v142
	s_nop 0
	v_mul_f32_e32 v142, v138, v142
	s_nop 0
	v_cvt_pk_bf16_f32 v138, v139, v140
	s_nop 0
	v_cvt_pk_bf16_f32 v139, v141, v142
	ds_write_b64 v131, v[138:139] offset:96
	v_mov_b32_e32 v138, v149
	v_mul_f32_e32 v139, v66, v138
	v_mul_f32_e32 v140, 0xbfb8aa3b, v139
	v_exp_f32_e32 v140, v140
	s_nop 0
	v_add_f32_e32 v140, 1.0, v140
	v_rcp_f32_e32 v140, v140
	s_nop 0
	v_mul_f32_e32 v139, v139, v140
	v_mul_f32_e32 v140, v67, v138
	v_mul_f32_e32 v141, 0xbfb8aa3b, v140
	v_exp_f32_e32 v141, v141
	s_nop 0
	v_add_f32_e32 v141, 1.0, v141
	v_rcp_f32_e32 v141, v141
	s_nop 0
	v_mul_f32_e32 v140, v140, v141
	v_mul_f32_e32 v141, v68, v138
	v_mul_f32_e32 v142, 0xbfb8aa3b, v141
	v_exp_f32_e32 v142, v142
	v_mul_f32_e32 v138, v69, v138
	v_add_f32_e32 v142, 1.0, v142
	v_rcp_f32_e32 v142, v142
	s_nop 0
	v_mul_f32_e32 v141, v141, v142
	v_mul_f32_e32 v142, 0xbfb8aa3b, v138
	v_exp_f32_e32 v142, v142
	s_nop 0
	v_add_f32_e32 v142, 1.0, v142
	v_rcp_f32_e32 v142, v142
	s_nop 0
	v_mul_f32_e32 v142, v138, v142
	s_nop 0
	v_cvt_pk_bf16_f32 v138, v139, v140
	s_nop 0
	v_cvt_pk_bf16_f32 v139, v141, v142
	ds_write_b64 v131, v[138:139] offset:8800
	v_mov_b32_e32 v138, v150
	v_mul_f32_e32 v139, v34, v138
	v_mul_f32_e32 v140, 0xbfb8aa3b, v139
	v_exp_f32_e32 v140, v140
	s_nop 0
	v_add_f32_e32 v140, 1.0, v140
	v_rcp_f32_e32 v140, v140
	s_nop 0
	v_mul_f32_e32 v139, v139, v140
	v_mul_f32_e32 v140, v35, v138
	v_mul_f32_e32 v141, 0xbfb8aa3b, v140
	v_exp_f32_e32 v141, v141
	s_nop 0
	v_add_f32_e32 v141, 1.0, v141
	v_rcp_f32_e32 v141, v141
	s_nop 0
	v_mul_f32_e32 v140, v140, v141
	v_mul_f32_e32 v141, v36, v138
	v_mul_f32_e32 v142, 0xbfb8aa3b, v141
	v_exp_f32_e32 v142, v142
	v_mul_f32_e32 v138, v37, v138
	v_add_f32_e32 v142, 1.0, v142
	v_rcp_f32_e32 v142, v142
	s_nop 0
	v_mul_f32_e32 v141, v141, v142
	v_mul_f32_e32 v142, 0xbfb8aa3b, v138
	v_exp_f32_e32 v142, v142
	s_nop 0
	v_add_f32_e32 v142, 1.0, v142
	v_rcp_f32_e32 v142, v142
	s_nop 0
	v_mul_f32_e32 v142, v138, v142
	s_nop 0
	v_cvt_pk_bf16_f32 v138, v139, v140
	s_nop 0
	v_cvt_pk_bf16_f32 v139, v141, v142
	ds_write_b64 v130, v[138:139] offset:61024
	v_mov_b32_e32 v138, v151
	v_mul_f32_e32 v139, v2, v138
	v_mul_f32_e32 v140, 0xbfb8aa3b, v139
	v_exp_f32_e32 v140, v140
	s_nop 0
	v_add_f32_e32 v140, 1.0, v140
	v_rcp_f32_e32 v140, v140
	s_nop 0
	v_mul_f32_e32 v139, v139, v140
	v_mul_f32_e32 v140, v3, v138
	v_mul_f32_e32 v141, 0xbfb8aa3b, v140
	v_exp_f32_e32 v141, v141
	s_nop 0
	v_add_f32_e32 v141, 1.0, v141
	v_rcp_f32_e32 v141, v141
	s_nop 0
	v_mul_f32_e32 v140, v140, v141
	v_mul_f32_e32 v141, v4, v138
	v_mul_f32_e32 v142, 0xbfb8aa3b, v141
	v_exp_f32_e32 v142, v142
	v_mul_f32_e32 v138, v5, v138
	v_add_f32_e32 v142, 1.0, v142
	v_rcp_f32_e32 v142, v142
	s_nop 0
	v_mul_f32_e32 v141, v141, v142
	v_mul_f32_e32 v142, 0xbfb8aa3b, v138
	v_exp_f32_e32 v142, v142
	s_nop 0
	v_add_f32_e32 v142, 1.0, v142
	v_rcp_f32_e32 v142, v142
	s_nop 0
	v_mul_f32_e32 v142, v138, v142
	s_nop 0
	v_cvt_pk_bf16_f32 v138, v139, v140
	s_nop 0
	v_cvt_pk_bf16_f32 v139, v141, v142
	ds_write_b64 v137, v[138:139] offset:8800
	v_mov_b32_e32 v138, v148
	v_mul_f32_e32 v139, v126, v138
	v_mul_f32_e32 v140, 0xbfb8aa3b, v139
	v_exp_f32_e32 v140, v140
	s_nop 0
	v_add_f32_e32 v140, 1.0, v140
	v_rcp_f32_e32 v140, v140
	s_nop 0
	v_mul_f32_e32 v139, v139, v140
	v_mul_f32_e32 v140, v127, v138
	v_mul_f32_e32 v141, 0xbfb8aa3b, v140
	v_exp_f32_e32 v141, v141
	s_nop 0
	v_add_f32_e32 v141, 1.0, v141
	v_rcp_f32_e32 v141, v141
	s_nop 0
	v_mul_f32_e32 v140, v140, v141
	v_mul_f32_e32 v141, v128, v138
	v_mul_f32_e32 v142, 0xbfb8aa3b, v141
	v_exp_f32_e32 v142, v142
	v_mul_f32_e32 v138, v129, v138
	v_add_f32_e32 v142, 1.0, v142
	v_rcp_f32_e32 v142, v142
	s_nop 0
	v_mul_f32_e32 v141, v141, v142
; __device__ __forceinline__ float siluf(float x) { return x * __builtin_amdgcn_rcpf(1.f + __expf(-x)); }
; #define STAGE_TILE_F(XFORM) do { SW_BEGIN f32x4 v = acc[ai][bj][m][n2]; XFORM; \
;     *(u32x2*)(smem + mrow * SPITCH + nc0 * 2) = u32x2{cvtpk_t(v[0], v[1]), cvtpk_t(v[2], v[3])}; LOOP_END __syncthreads(); } while (0)
; template <int kind> __device__ __forceinline__ void gemm_phase_n(const Params& P, int layer, int b, const int wv) {
;     ...
;                 } else {
;                     STAGE_TILE_F(const float r = rs_lds[mrow]; v[0] = siluf(v[0] * r); v[1] = siluf(v[1] * r); v[2] = siluf(v[2] * r); v[3] = siluf(v[3] * r));
;                     u16* dst = (u16*)(ws + O_SG) + (size_t)t0 * 2048 + (pn - 16) * 256;
;                     DRAIN_BEGIN *(u32x4*)(dst + (size_t)row * 2048 + chunk * 8) = w; LOOP_END
	v_mul_f32_e32 v142, 0xbfb8aa3b, v138
	v_exp_f32_e32 v142, v142
	s_nop 0
	v_add_f32_e32 v142, 1.0, v142
	v_rcp_f32_e32 v142, v142
	s_nop 0
	v_mul_f32_e32 v142, v138, v142
	s_nop 0
	v_cvt_pk_bf16_f32 v138, v139, v140
	s_nop 0
	v_cvt_pk_bf16_f32 v139, v141, v142
	ds_write_b64 v131, v[138:139] offset:256
	v_mov_b32_e32 v138, v149
	v_mul_f32_e32 v139, v94, v138
	v_mul_f32_e32 v140, 0xbfb8aa3b, v139
	v_exp_f32_e32 v140, v140
	s_nop 0
	v_add_f32_e32 v140, 1.0, v140
	v_rcp_f32_e32 v140, v140
	s_nop 0
	v_mul_f32_e32 v139, v139, v140
	v_mul_f32_e32 v140, v95, v138
	v_mul_f32_e32 v141, 0xbfb8aa3b, v140
	v_exp_f32_e32 v141, v141
	s_nop 0
	v_add_f32_e32 v141, 1.0, v141
	v_rcp_f32_e32 v141, v141
	s_nop 0
	v_mul_f32_e32 v140, v140, v141
	v_mul_f32_e32 v141, v96, v138
	v_mul_f32_e32 v142, 0xbfb8aa3b, v141
	v_exp_f32_e32 v142, v142
	v_mul_f32_e32 v138, v97, v138
	v_add_f32_e32 v142, 1.0, v142
	v_rcp_f32_e32 v142, v142
	s_nop 0
	v_mul_f32_e32 v141, v141, v142
	v_mul_f32_e32 v142, 0xbfb8aa3b, v138
	v_exp_f32_e32 v142, v142
	s_nop 0
	v_add_f32_e32 v142, 1.0, v142
	v_rcp_f32_e32 v142, v142
	s_nop 0
	v_mul_f32_e32 v142, v138, v142
	s_nop 0
	v_cvt_pk_bf16_f32 v138, v139, v140
	s_nop 0
	v_cvt_pk_bf16_f32 v139, v141, v142
	ds_write_b64 v131, v[138:139] offset:8960
	v_mov_b32_e32 v138, v150
	v_mul_f32_e32 v139, v62, v138
	v_mul_f32_e32 v140, 0xbfb8aa3b, v139
	v_exp_f32_e32 v140, v140
	s_nop 0
	v_add_f32_e32 v140, 1.0, v140
	v_rcp_f32_e32 v140, v140
	s_nop 0
	v_mul_f32_e32 v139, v139, v140
	v_mul_f32_e32 v140, v63, v138
	v_mul_f32_e32 v141, 0xbfb8aa3b, v140
	v_exp_f32_e32 v141, v141
	s_nop 0
	v_add_f32_e32 v141, 1.0, v141
	v_rcp_f32_e32 v141, v141
	s_nop 0
	v_mul_f32_e32 v140, v140, v141
	v_mul_f32_e32 v141, v64, v138
	v_mul_f32_e32 v142, 0xbfb8aa3b, v141
	v_exp_f32_e32 v142, v142
	v_mul_f32_e32 v138, v65, v138
	v_add_f32_e32 v142, 1.0, v142
	v_rcp_f32_e32 v142, v142
	s_nop 0
	v_mul_f32_e32 v141, v141, v142
	v_mul_f32_e32 v142, 0xbfb8aa3b, v138
	v_exp_f32_e32 v142, v142
	s_nop 0
	v_add_f32_e32 v142, 1.0, v142
	v_rcp_f32_e32 v142, v142
	s_nop 0
	v_mul_f32_e32 v142, v138, v142
	s_nop 0
	v_cvt_pk_bf16_f32 v138, v139, v140
	s_nop 0
	v_cvt_pk_bf16_f32 v139, v141, v142
	ds_write_b64 v130, v[138:139] offset:61184
	v_mov_b32_e32 v138, v151
	v_mul_f32_e32 v139, v30, v138
	v_mul_f32_e32 v140, 0xbfb8aa3b, v139
	v_exp_f32_e32 v140, v140
	s_nop 0
	v_add_f32_e32 v140, 1.0, v140
	v_rcp_f32_e32 v140, v140
	s_nop 0
	v_mul_f32_e32 v139, v139, v140
	v_mul_f32_e32 v140, v31, v138
	v_mul_f32_e32 v141, 0xbfb8aa3b, v140
	v_exp_f32_e32 v141, v141
	s_nop 0
	v_add_f32_e32 v141, 1.0, v141
	v_rcp_f32_e32 v141, v141
	s_nop 0
	v_mul_f32_e32 v140, v140, v141
	v_mul_f32_e32 v141, v32, v138
	v_mul_f32_e32 v142, 0xbfb8aa3b, v141
	v_exp_f32_e32 v142, v142
	v_mul_f32_e32 v138, v33, v138
	v_add_f32_e32 v142, 1.0, v142
	v_rcp_f32_e32 v142, v142
	s_nop 0
	v_mul_f32_e32 v141, v141, v142
	v_mul_f32_e32 v142, 0xbfb8aa3b, v138
	v_exp_f32_e32 v142, v142
	s_nop 0
	v_add_f32_e32 v142, 1.0, v142
	v_rcp_f32_e32 v142, v142
	s_nop 0
	v_mul_f32_e32 v142, v138, v142
	s_nop 0
	v_cvt_pk_bf16_f32 v138, v139, v140
	s_nop 0
	v_cvt_pk_bf16_f32 v139, v141, v142
	ds_write_b64 v137, v[138:139] offset:8960
	v_mov_b32_e32 v138, v148
	v_mul_f32_e32 v139, v118, v138
	v_mul_f32_e32 v140, 0xbfb8aa3b, v139
	v_exp_f32_e32 v140, v140
	s_nop 0
	v_add_f32_e32 v140, 1.0, v140
	v_rcp_f32_e32 v140, v140
	s_nop 0
	v_mul_f32_e32 v139, v139, v140
	v_mul_f32_e32 v140, v119, v138
	v_mul_f32_e32 v141, 0xbfb8aa3b, v140
	v_exp_f32_e32 v141, v141
	s_nop 0
	v_add_f32_e32 v141, 1.0, v141
	v_rcp_f32_e32 v141, v141
	s_nop 0
	v_mul_f32_e32 v140, v140, v141
	v_mul_f32_e32 v141, v120, v138
	v_mul_f32_e32 v142, 0xbfb8aa3b, v141
	v_exp_f32_e32 v142, v142
	v_mul_f32_e32 v138, v121, v138
	v_add_f32_e32 v142, 1.0, v142
	v_rcp_f32_e32 v142, v142
	s_nop 0
	v_mul_f32_e32 v141, v141, v142
	v_mul_f32_e32 v142, 0xbfb8aa3b, v138
	v_exp_f32_e32 v142, v142
	s_nop 0
	v_add_f32_e32 v142, 1.0, v142
	v_rcp_f32_e32 v142, v142
	s_nop 0
	v_mul_f32_e32 v142, v138, v142
	s_nop 0
	v_cvt_pk_bf16_f32 v138, v139, v140
	s_nop 0
	v_cvt_pk_bf16_f32 v139, v141, v142
	ds_write_b64 v131, v[138:139] offset:288
	v_mov_b32_e32 v138, v149
	v_mul_f32_e32 v139, v86, v138
	v_mul_f32_e32 v140, 0xbfb8aa3b, v139
	v_exp_f32_e32 v140, v140
	s_nop 0
	v_add_f32_e32 v140, 1.0, v140
	v_rcp_f32_e32 v140, v140
	s_nop 0
	v_mul_f32_e32 v139, v139, v140
	v_mul_f32_e32 v140, v87, v138
	v_mul_f32_e32 v141, 0xbfb8aa3b, v140
	v_exp_f32_e32 v141, v141
	s_nop 0
	v_add_f32_e32 v141, 1.0, v141
	v_rcp_f32_e32 v141, v141
	s_nop 0
	v_mul_f32_e32 v140, v140, v141
	v_mul_f32_e32 v141, v88, v138
	v_mul_f32_e32 v142, 0xbfb8aa3b, v141
	v_exp_f32_e32 v142, v142
	v_mul_f32_e32 v138, v89, v138
	v_add_f32_e32 v142, 1.0, v142
	v_rcp_f32_e32 v142, v142
	s_nop 0
	v_mul_f32_e32 v141, v141, v142
	v_mul_f32_e32 v142, 0xbfb8aa3b, v138
	v_exp_f32_e32 v142, v142
	s_nop 0
	v_add_f32_e32 v142, 1.0, v142
	v_rcp_f32_e32 v142, v142
	s_nop 0
	v_mul_f32_e32 v142, v138, v142
	s_nop 0
	v_cvt_pk_bf16_f32 v138, v139, v140
	s_nop 0
	v_cvt_pk_bf16_f32 v139, v141, v142
	ds_write_b64 v131, v[138:139] offset:8992
	v_mov_b32_e32 v138, v150
	v_mul_f32_e32 v139, v54, v138
	v_mul_f32_e32 v140, 0xbfb8aa3b, v139
	v_exp_f32_e32 v140, v140
	s_nop 0
	v_add_f32_e32 v140, 1.0, v140
	v_rcp_f32_e32 v140, v140
	s_nop 0
	v_mul_f32_e32 v139, v139, v140
	v_mul_f32_e32 v140, v55, v138
	v_mul_f32_e32 v141, 0xbfb8aa3b, v140
	v_exp_f32_e32 v141, v141
	s_nop 0
	v_add_f32_e32 v141, 1.0, v141
	v_rcp_f32_e32 v141, v141
	s_nop 0
	v_mul_f32_e32 v140, v140, v141
	v_mul_f32_e32 v141, v56, v138
	v_mul_f32_e32 v142, 0xbfb8aa3b, v141
	v_exp_f32_e32 v142, v142
	v_mul_f32_e32 v138, v57, v138
; __device__ __forceinline__ float siluf(float x) { return x * __builtin_amdgcn_rcpf(1.f + __expf(-x)); }
; #define STAGE_TILE_F(XFORM) do { SW_BEGIN f32x4 v = acc[ai][bj][m][n2]; XFORM; \
;     *(u32x2*)(smem + mrow * SPITCH + nc0 * 2) = u32x2{cvtpk_t(v[0], v[1]), cvtpk_t(v[2], v[3])}; LOOP_END __syncthreads(); } while (0)
; template <int kind> __device__ __forceinline__ void gemm_phase_n(const Params& P, int layer, int b, const int wv) {
;     ...
;                 } else {
;                     STAGE_TILE_F(const float r = rs_lds[mrow]; v[0] = siluf(v[0] * r); v[1] = siluf(v[1] * r); v[2] = siluf(v[2] * r); v[3] = siluf(v[3] * r));
;                     u16* dst = (u16*)(ws + O_SG) + (size_t)t0 * 2048 + (pn - 16) * 256;
;                     DRAIN_BEGIN *(u32x4*)(dst + (size_t)row * 2048 + chunk * 8) = w; LOOP_END
	v_add_f32_e32 v142, 1.0, v142
	v_rcp_f32_e32 v142, v142
	s_nop 0
	v_mul_f32_e32 v141, v141, v142
	v_mul_f32_e32 v142, 0xbfb8aa3b, v138
	v_exp_f32_e32 v142, v142
	s_nop 0
	v_add_f32_e32 v142, 1.0, v142
	v_rcp_f32_e32 v142, v142
	s_nop 0
	v_mul_f32_e32 v142, v138, v142
	s_nop 0
	v_cvt_pk_bf16_f32 v138, v139, v140
	s_nop 0
	v_cvt_pk_bf16_f32 v139, v141, v142
	ds_write_b64 v130, v[138:139] offset:61216
	v_mov_b32_e32 v138, v151
	v_mul_f32_e32 v139, v22, v138
	v_mul_f32_e32 v140, 0xbfb8aa3b, v139
	v_exp_f32_e32 v140, v140
	s_nop 0
	v_add_f32_e32 v140, 1.0, v140
	v_rcp_f32_e32 v140, v140
	s_nop 0
	v_mul_f32_e32 v139, v139, v140
	v_mul_f32_e32 v140, v23, v138
	v_mul_f32_e32 v141, 0xbfb8aa3b, v140
	v_exp_f32_e32 v141, v141
	s_nop 0
	v_add_f32_e32 v141, 1.0, v141
	v_rcp_f32_e32 v141, v141
	s_nop 0
	v_mul_f32_e32 v140, v140, v141
	v_mul_f32_e32 v141, v24, v138
	v_mul_f32_e32 v142, 0xbfb8aa3b, v141
	v_exp_f32_e32 v142, v142
	v_mul_f32_e32 v138, v25, v138
	v_add_f32_e32 v142, 1.0, v142
	v_rcp_f32_e32 v142, v142
	s_nop 0
	v_mul_f32_e32 v141, v141, v142
	v_mul_f32_e32 v142, 0xbfb8aa3b, v138
	v_exp_f32_e32 v142, v142
	s_nop 0
	v_add_f32_e32 v142, 1.0, v142
	v_rcp_f32_e32 v142, v142
	s_nop 0
	v_mul_f32_e32 v142, v138, v142
	s_nop 0
	v_cvt_pk_bf16_f32 v138, v139, v140
	s_nop 0
	v_cvt_pk_bf16_f32 v139, v141, v142
	ds_write_b64 v137, v[138:139] offset:8992
	v_mov_b32_e32 v138, v148
	v_mul_f32_e32 v139, v110, v138
	v_mul_f32_e32 v140, 0xbfb8aa3b, v139
	v_exp_f32_e32 v140, v140
	s_nop 0
	v_add_f32_e32 v140, 1.0, v140
	v_rcp_f32_e32 v140, v140
	s_nop 0
	v_mul_f32_e32 v139, v139, v140
	v_mul_f32_e32 v140, v111, v138
	v_mul_f32_e32 v141, 0xbfb8aa3b, v140
	v_exp_f32_e32 v141, v141
	s_nop 0
	v_add_f32_e32 v141, 1.0, v141
	v_rcp_f32_e32 v141, v141
	s_nop 0
	v_mul_f32_e32 v140, v140, v141
	v_mul_f32_e32 v141, v112, v138
	v_mul_f32_e32 v142, 0xbfb8aa3b, v141
	v_exp_f32_e32 v142, v142
	v_mul_f32_e32 v138, v113, v138
	v_add_f32_e32 v142, 1.0, v142
	v_rcp_f32_e32 v142, v142
	s_nop 0
	v_mul_f32_e32 v141, v141, v142
	v_mul_f32_e32 v142, 0xbfb8aa3b, v138
	v_exp_f32_e32 v142, v142
	s_nop 0
	v_add_f32_e32 v142, 1.0, v142
	v_rcp_f32_e32 v142, v142
	s_nop 0
	v_mul_f32_e32 v142, v138, v142
	s_nop 0
	v_cvt_pk_bf16_f32 v138, v139, v140
	s_nop 0
	v_cvt_pk_bf16_f32 v139, v141, v142
	ds_write_b64 v131, v[138:139] offset:320
	v_mov_b32_e32 v138, v149
	v_mul_f32_e32 v139, v78, v138
	v_mul_f32_e32 v140, 0xbfb8aa3b, v139
	v_exp_f32_e32 v140, v140
	s_nop 0
	v_add_f32_e32 v140, 1.0, v140
	v_rcp_f32_e32 v140, v140
	s_nop 0
	v_mul_f32_e32 v139, v139, v140
	v_mul_f32_e32 v140, v79, v138
	v_mul_f32_e32 v141, 0xbfb8aa3b, v140
	v_exp_f32_e32 v141, v141
	s_nop 0
	v_add_f32_e32 v141, 1.0, v141
	v_rcp_f32_e32 v141, v141
	s_nop 0
	v_mul_f32_e32 v140, v140, v141
	v_mul_f32_e32 v141, v80, v138
	v_mul_f32_e32 v142, 0xbfb8aa3b, v141
	v_exp_f32_e32 v142, v142
	v_mul_f32_e32 v138, v81, v138
	v_add_f32_e32 v142, 1.0, v142
	v_rcp_f32_e32 v142, v142
	s_nop 0
	v_mul_f32_e32 v141, v141, v142
	v_mul_f32_e32 v142, 0xbfb8aa3b, v138
	v_exp_f32_e32 v142, v142
	s_nop 0
	v_add_f32_e32 v142, 1.0, v142
	v_rcp_f32_e32 v142, v142
	s_nop 0
	v_mul_f32_e32 v142, v138, v142
	s_nop 0
	v_cvt_pk_bf16_f32 v138, v139, v140
	s_nop 0
	v_cvt_pk_bf16_f32 v139, v141, v142
	ds_write_b64 v131, v[138:139] offset:9024
	v_mov_b32_e32 v138, v150
	v_mul_f32_e32 v139, v46, v138
	v_mul_f32_e32 v140, 0xbfb8aa3b, v139
	v_exp_f32_e32 v140, v140
	s_nop 0
	v_add_f32_e32 v140, 1.0, v140
	v_rcp_f32_e32 v140, v140
	s_nop 0
	v_mul_f32_e32 v139, v139, v140
	v_mul_f32_e32 v140, v47, v138
	v_mul_f32_e32 v141, 0xbfb8aa3b, v140
	v_exp_f32_e32 v141, v141
	s_nop 0
	v_add_f32_e32 v141, 1.0, v141
	v_rcp_f32_e32 v141, v141
	s_nop 0
	v_mul_f32_e32 v140, v140, v141
	v_mul_f32_e32 v141, v48, v138
	v_mul_f32_e32 v142, 0xbfb8aa3b, v141
	v_exp_f32_e32 v142, v142
	v_mul_f32_e32 v138, v49, v138
	v_add_f32_e32 v142, 1.0, v142
	v_rcp_f32_e32 v142, v142
	s_nop 0
	v_mul_f32_e32 v141, v141, v142
	v_mul_f32_e32 v142, 0xbfb8aa3b, v138
	v_exp_f32_e32 v142, v142
	s_nop 0
	v_add_f32_e32 v142, 1.0, v142
	v_rcp_f32_e32 v142, v142
	s_nop 0
	v_mul_f32_e32 v142, v138, v142
	s_nop 0
	v_cvt_pk_bf16_f32 v138, v139, v140
	s_nop 0
	v_cvt_pk_bf16_f32 v139, v141, v142
	ds_write_b64 v130, v[138:139] offset:61248
	v_mov_b32_e32 v138, v151
	v_mul_f32_e32 v139, v14, v138
	v_mul_f32_e32 v140, 0xbfb8aa3b, v139
	v_exp_f32_e32 v140, v140
	s_nop 0
	v_add_f32_e32 v140, 1.0, v140
	v_rcp_f32_e32 v140, v140
	s_nop 0
	v_mul_f32_e32 v139, v139, v140
	v_mul_f32_e32 v140, v15, v138
	v_mul_f32_e32 v141, 0xbfb8aa3b, v140
	v_exp_f32_e32 v141, v141
	s_nop 0
	v_add_f32_e32 v141, 1.0, v141
	v_rcp_f32_e32 v141, v141
	s_nop 0
	v_mul_f32_e32 v140, v140, v141
	v_mul_f32_e32 v141, v16, v138
	v_mul_f32_e32 v142, 0xbfb8aa3b, v141
	v_exp_f32_e32 v142, v142
; __device__ __forceinline__ float siluf(float x) { return x * __builtin_amdgcn_rcpf(1.f + __expf(-x)); }
; #define STAGE_TILE_F(XFORM) do { SW_BEGIN f32x4 v = acc[ai][bj][m][n2]; XFORM; \
;     *(u32x2*)(smem + mrow * SPITCH + nc0 * 2) = u32x2{cvtpk_t(v[0], v[1]), cvtpk_t(v[2], v[3])}; LOOP_END __syncthreads(); } while (0)
; template <int kind> __device__ __forceinline__ void gemm_phase_n(const Params& P, int layer, int b, const int wv) {
;     ...
;                 } else {
;                     STAGE_TILE_F(const float r = rs_lds[mrow]; v[0] = siluf(v[0] * r); v[1] = siluf(v[1] * r); v[2] = siluf(v[2] * r); v[3] = siluf(v[3] * r));
;                     u16* dst = (u16*)(ws + O_SG) + (size_t)t0 * 2048 + (pn - 16) * 256;
;                     DRAIN_BEGIN *(u32x4*)(dst + (size_t)row * 2048 + chunk * 8) = w; LOOP_END
	v_mul_f32_e32 v138, v17, v138
	v_add_f32_e32 v142, 1.0, v142
	v_rcp_f32_e32 v142, v142
	s_nop 0
	v_mul_f32_e32 v141, v141, v142
	v_mul_f32_e32 v142, 0xbfb8aa3b, v138
	v_exp_f32_e32 v142, v142
	s_nop 0
	v_add_f32_e32 v142, 1.0, v142
	v_rcp_f32_e32 v142, v142
	s_nop 0
	v_mul_f32_e32 v142, v138, v142
	s_nop 0
	v_cvt_pk_bf16_f32 v138, v139, v140
	s_nop 0
	v_cvt_pk_bf16_f32 v139, v141, v142
	ds_write_b64 v137, v[138:139] offset:9024
	v_mov_b32_e32 v138, v148
	v_mul_f32_e32 v139, v106, v138
	v_mul_f32_e32 v140, 0xbfb8aa3b, v139
	v_exp_f32_e32 v140, v140
	s_nop 0
	v_add_f32_e32 v140, 1.0, v140
	v_rcp_f32_e32 v140, v140
	s_nop 0
	v_mul_f32_e32 v139, v139, v140
	v_mul_f32_e32 v140, v107, v138
	v_mul_f32_e32 v141, 0xbfb8aa3b, v140
	v_exp_f32_e32 v141, v141
	s_nop 0
	v_add_f32_e32 v141, 1.0, v141
	v_rcp_f32_e32 v141, v141
	s_nop 0
	v_mul_f32_e32 v140, v140, v141
	v_mul_f32_e32 v141, v108, v138
	v_mul_f32_e32 v142, 0xbfb8aa3b, v141
	v_exp_f32_e32 v142, v142
	v_mul_f32_e32 v138, v109, v138
	v_add_f32_e32 v142, 1.0, v142
	v_rcp_f32_e32 v142, v142
	s_nop 0
	v_mul_f32_e32 v141, v141, v142
	v_mul_f32_e32 v142, 0xbfb8aa3b, v138
	v_exp_f32_e32 v142, v142
	s_nop 0
	v_add_f32_e32 v142, 1.0, v142
	v_rcp_f32_e32 v142, v142
	s_nop 0
	v_mul_f32_e32 v142, v138, v142
	s_nop 0
	v_cvt_pk_bf16_f32 v138, v139, v140
	s_nop 0
	v_cvt_pk_bf16_f32 v139, v141, v142
	ds_write_b64 v131, v[138:139] offset:352
	v_mov_b32_e32 v138, v149
	v_mul_f32_e32 v139, v74, v138
	v_mul_f32_e32 v140, 0xbfb8aa3b, v139
	v_exp_f32_e32 v140, v140
	s_nop 0
	v_add_f32_e32 v140, 1.0, v140
	v_rcp_f32_e32 v140, v140
	s_nop 0
	v_mul_f32_e32 v139, v139, v140
	v_mul_f32_e32 v140, v75, v138
	v_mul_f32_e32 v141, 0xbfb8aa3b, v140
	v_exp_f32_e32 v141, v141
	s_nop 0
	v_add_f32_e32 v141, 1.0, v141
	v_rcp_f32_e32 v141, v141
	s_nop 0
	v_mul_f32_e32 v140, v140, v141
	v_mul_f32_e32 v141, v76, v138
	v_mul_f32_e32 v142, 0xbfb8aa3b, v141
	v_exp_f32_e32 v142, v142
	v_mul_f32_e32 v138, v77, v138
	v_add_f32_e32 v142, 1.0, v142
	v_rcp_f32_e32 v142, v142
	s_nop 0
	v_mul_f32_e32 v141, v141, v142
	v_mul_f32_e32 v142, 0xbfb8aa3b, v138
	v_exp_f32_e32 v142, v142
	s_nop 0
	v_add_f32_e32 v142, 1.0, v142
	v_rcp_f32_e32 v142, v142
	s_nop 0
	v_mul_f32_e32 v142, v138, v142
	s_nop 0
	v_cvt_pk_bf16_f32 v138, v139, v140
	s_nop 0
	v_cvt_pk_bf16_f32 v139, v141, v142
	ds_write_b64 v131, v[138:139] offset:9056
	v_mov_b32_e32 v131, v150
	v_mul_f32_e32 v138, v42, v131
	v_mul_f32_e32 v139, 0xbfb8aa3b, v138
	v_exp_f32_e32 v139, v139
	s_nop 0
	v_add_f32_e32 v139, 1.0, v139
	v_rcp_f32_e32 v139, v139
	s_nop 0
	v_mul_f32_e32 v138, v138, v139
	v_mul_f32_e32 v139, v43, v131
	v_mul_f32_e32 v140, 0xbfb8aa3b, v139
	v_exp_f32_e32 v140, v140
	s_nop 0
	v_add_f32_e32 v140, 1.0, v140
	v_rcp_f32_e32 v140, v140
	s_nop 0
	v_mul_f32_e32 v139, v139, v140
	v_mul_f32_e32 v140, v44, v131
	v_mul_f32_e32 v141, 0xbfb8aa3b, v140
	v_exp_f32_e32 v141, v141
	v_mul_f32_e32 v131, v45, v131
	s_nop 0
	v_cvt_pk_bf16_f32 v138, v138, v139
	v_add_f32_e32 v141, 1.0, v141
	v_rcp_f32_e32 v141, v141
	s_nop 0
	v_mul_f32_e32 v140, v140, v141
	v_mul_f32_e32 v141, 0xbfb8aa3b, v131
	v_exp_f32_e32 v141, v141
	s_nop 0
	v_add_f32_e32 v141, 1.0, v141
	v_rcp_f32_e32 v141, v141
	s_nop 0
	v_mul_f32_e32 v131, v131, v141
	s_nop 0
	v_cvt_pk_bf16_f32 v139, v140, v131
	ds_write_b64 v130, v[138:139] offset:61280
	v_mov_b32_e32 v0, v151
	v_mul_f32_e32 v130, v6, v0
	v_mul_f32_e32 v131, 0xbfb8aa3b, v130
	v_exp_f32_e32 v131, v131
	s_nop 0
	v_add_f32_e32 v131, 1.0, v131
	v_rcp_f32_e32 v131, v131
	s_nop 0
	v_mul_f32_e32 v130, v130, v131
	v_mul_f32_e32 v131, v7, v0
	v_mul_f32_e32 v138, 0xbfb8aa3b, v131
	v_exp_f32_e32 v138, v138
	s_nop 0
	v_add_f32_e32 v138, 1.0, v138
	v_rcp_f32_e32 v138, v138
	s_nop 0
	v_mul_f32_e32 v131, v131, v138
	v_mul_f32_e32 v138, v8, v0
	v_mul_f32_e32 v139, 0xbfb8aa3b, v138
	v_exp_f32_e32 v139, v139
	v_mul_f32_e32 v0, v9, v0
	s_nop 0
	v_cvt_pk_bf16_f32 v130, v130, v131
	v_add_f32_e32 v139, 1.0, v139
	v_rcp_f32_e32 v139, v139
	s_nop 0
	v_mul_f32_e32 v138, v138, v139
	v_mul_f32_e32 v139, 0xbfb8aa3b, v0
	v_exp_f32_e32 v139, v139
	s_nop 0
	v_add_f32_e32 v139, 1.0, v139
	v_rcp_f32_e32 v139, v139
	s_nop 0
	v_mul_f32_e32 v0, v0, v139
	s_nop 0
	v_cvt_pk_bf16_f32 v131, v138, v0
	v_ashrrev_i32_e32 v138, 5, v132
	v_ashrrev_i32_e32 v139, 31, v138
	ds_write_b64 v137, v[130:131] offset:9056
	v_lshlrev_b64 v[130:131], 12, v[138:139]
	v_lshlrev_b32_e32 v0, 4, v132
	v_lshl_add_u64 v[130:131], v[130:131], 0, s[2:3]
	s_lshl_b64 s[2:3], s[14:15], 1
	v_and_b32_e32 v0, 0x1f0, v0
	s_add_u32 s2, s21, s2
	v_or_b32_e32 v130, v130, v0
	s_addc_u32 s3, s22, s3
	v_lshl_add_u64 v[130:131], s[2:3], 0, v[130:131]
	s_movk_i32 s2, 0x220
	v_mul_lo_u32 v137, v138, s2
	v_add3_u32 v0, v137, v0, 0
	s_mov_b64 s[2:3], 0
	s_waitcnt vmcnt(0) lgkmcnt(0)
	s_barrier
